# SB step loop: O-accumulator copies only on tile-skip path, -z clamp fused into one v_min with SGPR constant
# speedup vs baseline: 1.1023x; 1.0055x over previous
; DEV void sb_block(const Params& p, int item) {
;     ...
;   for (int n = 0; n < nsteps; ++n) {
;     const int j = nsteps - 1 - n, buf = n & 3;
;     asm volatile("s_waitcnt vmcnt(8)" ::: "memory");
;     __builtin_amdgcn_s_barrier();
;     asm volatile("" ::: "memory");
;     { const int jn = j > 3 ? j - 3 : 0; SB_DMA(jn, (n + 3) & 3); }
.LBB0_543:
	s_mov_b32 s32, 0x42f00000
	s_max_i32 s0, s71, 3
	s_lshl_b32 s0, s0, 6
	s_waitcnt vmcnt(8)
	s_barrier
	s_add_i32 s92, s0, 0xffffff40
	s_add_i32 s0, s33, 0x18000
	s_and_b32 s0, s0, 0x18000
	v_lshl_add_u64 v[64:65], s[92:93], 1, v[180:181]
	v_add_u32_e32 v66, s0, v204
	s_mov_b64 s[66:67], -1
	s_and_b64 vcc, exec, s[90:91]
	s_cbranch_vccz .LBB0_551
	v_readlane_b32 s0, v252, 7
	v_add_u32_e32 v67, s3, v66
	v_readlane_b32 s1, v252, 8
	v_add_u32_e32 v67, 0x4000, v67
	s_nop 0
	v_lshl_add_u64 v[68:69], v[64:65], 0, s[0:1]
	v_readfirstlane_b32 s0, v67
	v_lshl_add_u64 v[68:69], v[68:69], 0, v[176:177]
	s_mov_b32 m0, s0
	s_nop 0
	global_load_lds_dwordx4 v[68:69], off
	s_cbranch_execz .LBB0_552

; DEV f32x16 mfma32(bf16x8 a, bf16x8 b, f32x16 c) { return __builtin_amdgcn_mfma_f32_32x32x16_bf16(a, b, c, 0, 0, 0); }
; template <bool DIAG>
; DEV void sb_tile(const char* lk, const char* lv, const int ko0, const int vo0, const bf16x8 (&qf)[8], f32x16 (&O)[4], float& accp,
;                  const int l31, const int hh) {
;   f32x16 z;
;   for (int g = 0; g < 16; ++g) z[g] = 0.f;
;   {
;     bf16x8 kf[8];
; #pragma unroll
;     for (int s = 0; s < 8; ++s) kf[s] = *(const bf16x8*)(lk + (ko0 ^ (32 * s)));
;     __builtin_amdgcn_sched_barrier(0);
; #pragma unroll
;     for (int s = 0; s < 8; ++s) z = mfma32(kf[s], qf[s], z);
;   }
;   bf16x8 vf[4][2];
; #pragma unroll
;   for (int d = 0; d < 4; ++d) { vf[d][0] = *(const bf16x8*)(lv + d * 4096 + vo0); vf[d][1] = *(const bf16x8*)(lv + d * 4096 + (vo0 ^ 32)); }
;   __builtin_amdgcn_sched_barrier(0);
;   float be[16], om[16];
; #pragma unroll
;   for (int g = 0; g < 16; ++g) {
;     const float e = __builtin_amdgcn_exp2f(fminf(-z[g], 120.f));
;     be[g] = __builtin_amdgcn_rcpf(1.f + e);
;     om[g] = e * be[g];
;     if (DIAG) { const int kl = (g & 3) + 8 * (g >> 2) + 4 * hh; if (kl >= l31) { be[g] = 0.f; om[g] = 1.f; } }
;   }
; DEV void sb_block(const Params& p, int item) {
;     ...
;     if (2 * j + 1 == qt) sb_tile<true>(lb_ + 32 * 256, lb_, ko0, vo0 ^ 64, qf, O, accp, l31, hh);
;     else if (2 * j + 1 < qt) sb_tile<false>(lb_ + 32 * 256, lb_, ko0, vo0 ^ 64, qf, O, accp, l31, hh);
.LBB0_559:
	s_and_b32 s0, s33, 0x18000
	s_add_i32 s92, s0, 0
	s_add_i32 s0, s74, s69
	v_mov_b32_e32 v168, v205
	v_mov_b32_e32 v193, v206
	s_cmp_lg_u32 s89, s69
	s_mov_b64 s[66:67], -1
	s_cbranch_scc0 .LBB0_563
	s_add_i32 s1, s0, 7
	s_cmp_ge_i32 s1, s75
	s_cbranch_scc1 .Lsb_skip_A0
	v_add_u32_e32 v64, s92, v168
	v_xad_u32 v68, v168, 32, s92
	ds_read_b128 v[64:67], v64 offset:8192
	ds_read_b128 v[80:83], v68 offset:8192
	v_xad_u32 v68, v168, 64, s92
	v_xor_b32_e32 v69, 0x60, v168
	v_add_u32_e32 v69, s92, v69
	ds_read_b128 v[84:87], v68 offset:8192
	ds_read_b128 v[88:91], v69 offset:8192
	v_xor_b32_e32 v68, 0x80, v168
	v_add_u32_e32 v68, s92, v68
	v_xor_b32_e32 v69, 0xa0, v168
	v_add_u32_e32 v69, s92, v69
	ds_read_b128 v[92:95], v68 offset:8192
	ds_read_b128 v[96:99], v69 offset:8192
	v_xor_b32_e32 v68, 0xc0, v168
	v_add_u32_e32 v68, s92, v68
	v_xor_b32_e32 v69, 0xe0, v168
	v_add_u32_e32 v69, s92, v69
	ds_read_b128 v[100:103], v68 offset:8192
	ds_read_b128 v[104:107], v69 offset:8192
	s_waitcnt lgkmcnt(0)
	v_mfma_f32_32x32x16_bf16 v[64:79], v[64:67], v[128:131], 0
	v_mfma_f32_32x32x16_bf16 v[64:79], v[80:83], v[132:135], v[64:79]
	v_xor_b32_e32 v80, 0x60, v193
	v_mfma_f32_32x32x16_bf16 v[64:79], v[84:87], v[136:139], v[64:79]
	v_mfma_f32_32x32x16_bf16 v[64:79], v[88:91], v[140:143], v[64:79]
	v_xad_u32 v88, v193, 64, s92
	v_add_u32_e32 v89, s92, v80
	v_mfma_f32_32x32x16_bf16 v[64:79], v[92:95], v[144:147], v[64:79]
	v_mfma_f32_32x32x16_bf16 v[64:79], v[96:99], v[148:151], v[64:79]
	v_mfma_f32_32x32x16_bf16 v[64:79], v[100:103], v[152:155], v[64:79]
	ds_read_b128 v[84:87], v88
	ds_read_b128 v[96:99], v88 offset:4096
	ds_read_b128 v[80:83], v89
	ds_read_b128 v[100:103], v89 offset:4096
	ds_read_b128 v[112:115], v88 offset:8192
	ds_read_b128 v[164:167], v88 offset:12288
	ds_read_b128 v[116:119], v89 offset:8192
	ds_read_b128 v[160:163], v89 offset:12288
	v_mfma_f32_32x32x16_bf16 v[64:79], v[104:107], v[156:159], v[64:79]
	s_nop 11
	v_min_f32_e64 v68, -v68, s32
	v_exp_f32_e32 v90, v68
	v_min_f32_e64 v68, -v69, s32
	v_exp_f32_e32 v91, v68
	v_add_f32_e32 v68, 1.0, v90
	v_min_f32_e64 v73, -v73, s32
	v_add_f32_e32 v69, 1.0, v91
	v_rcp_f32_e32 v68, v68
	v_rcp_f32_e32 v69, v69
	v_exp_f32_e32 v104, v73
	v_max_f32_e64 v73, -v74, -v74
	v_max_f32_e64 v74, -v75, -v75
	v_min_f32_e64 v72, -v72, s32
	v_min_f32_e32 v74, 0x42f00000, v74
	v_min_f32_e64 v75, -v77, s32
	v_max_f32_e64 v77, -v79, -v79
	v_and_b32_e32 v79, 64, v219
	v_exp_f32_e32 v72, v72
	v_exp_f32_e32 v105, v74
	v_max_f32_e64 v74, -v76, -v76
	v_exp_f32_e32 v76, v75
	v_max_f32_e64 v75, -v78, -v78
	v_xor_b32_e32 v78, 32, v219
	v_add_u32_e32 v79, 64, v79
	v_min_f32_e32 v73, 0x42f00000, v73
	v_cmp_lt_i32_e32 vcc, v78, v79
	v_pk_mul_f32 v[90:91], v[90:91], v[68:69]
	v_exp_f32_e32 v73, v73
	v_cndmask_b32_e32 v78, v219, v78, vcc
	v_lshlrev_b32_e32 v170, 2, v78
	v_pk_mul_f32 v[78:79], v[90:91], v[90:91] op_sel_hi:[0,1]
	v_add_f32_e32 v78, 1.0, v72
	v_rcp_f32_e32 v108, v78
	v_add_f32_e32 v78, 1.0, v104
	v_rcp_f32_e32 v110, v78
	v_add_f32_e32 v78, 1.0, v73
	v_rcp_f32_e32 v109, v78
	v_add_f32_e32 v78, 1.0, v105
	v_min_f32_e32 v74, 0x42f00000, v74
	v_rcp_f32_e32 v111, v78
	v_exp_f32_e32 v74, v74
	v_min_f32_e32 v75, 0x42f00000, v75
	v_exp_f32_e32 v75, v75
	v_min_f32_e32 v77, 0x42f00000, v77
	v_exp_f32_e32 v77, v77
	v_pk_mul_f32 v[72:73], v[72:73], v[108:109]
	v_pk_mul_f32 v[104:105], v[104:105], v[110:111]
	v_pk_mul_f32 v[120:121], v[72:73], v[104:105]
	v_add_f32_e32 v72, 1.0, v74
	v_rcp_f32_e32 v122, v72
	v_add_f32_e32 v72, 1.0, v76
	v_rcp_f32_e32 v124, v72
	v_add_f32_e32 v72, 1.0, v75
	v_min_f32_e64 v70, -v70, s32
	v_rcp_f32_e32 v123, v72
	v_add_f32_e32 v72, 1.0, v77
	v_exp_f32_e32 v92, v70
	v_rcp_f32_e32 v125, v72
	v_min_f32_e64 v70, -v71, s32
	v_min_f32_e64 v67, -v67, s32
	v_exp_f32_e32 v93, v70
	v_min_f32_e64 v64, -v64, s32
	v_exp_f32_e32 v196, v67
	v_exp_f32_e32 v88, v64
	v_pk_mul_f32 v[74:75], v[74:75], v[122:123]
	v_pk_mul_f32 v[76:77], v[76:77], v[124:125]
	v_add_f32_e32 v70, 1.0, v92
	v_pk_mul_f32 v[126:127], v[74:75], v[76:77]
	v_add_f32_e32 v71, 1.0, v93
	v_mul_f32_e32 v72, v126, v127
	v_add_f32_e32 v67, 1.0, v196
	v_rcp_f32_e32 v70, v70
	v_rcp_f32_e32 v71, v71
	v_pk_mul_f32 v[120:121], v[120:121], v[120:121] op_sel:[0,1] op_sel_hi:[1,0]
	ds_bpermute_b32 v74, v170, v72
	v_add_f32_e32 v64, 1.0, v88
	v_min_f32_e64 v66, -v66, s32
	v_rcp_f32_e32 v67, v67
	ds_bpermute_b32 v121, v170, v120
	v_rcp_f32_e32 v64, v64
	v_min_f32_e64 v65, -v65, s32
	v_exp_f32_e32 v94, v66
	v_exp_f32_e32 v169, v65
	v_pk_mul_f32 v[92:93], v[92:93], v[70:71]
	s_waitcnt lgkmcnt(0)
; DEV f32x16 mfma32(bf16x8 a, bf16x8 b, f32x16 c) { return __builtin_amdgcn_mfma_f32_32x32x16_bf16(a, b, c, 0, 0, 0); }
; template <bool DIAG>
; DEV void sb_tile(const char* lk, const char* lv, const int ko0, const int vo0, const bf16x8 (&qf)[8], f32x16 (&O)[4], float& accp,
;                  const int l31, const int hh) {
;     ...
;   float gp[4], pp[4], tot[4];
; #pragma unroll
;   for (int q = 0; q < 4; ++q) { gp[q] = (om[4 * q] * om[4 * q + 1]) * (om[4 * q + 2] * om[4 * q + 3]); pp[q] = __shfl_xor(gp[q], 32); tot[q] = gp[q] * pp[q]; }
;   float suf[4];
;   suf[3] = accp; suf[2] = suf[3] * tot[3]; suf[1] = suf[2] * tot[2]; suf[0] = suf[1] * tot[1];
;   accp = suf[0] * tot[0];
;   f32x16 w;
; #pragma unroll
;   for (int q = 0; q < 4; ++q) {
;     float a = suf[q] * (hh == 0 ? pp[q] : 1.f);
;     w[4 * q + 3] = be[4 * q + 3] * a; a *= om[4 * q + 3];
;     w[4 * q + 2] = be[4 * q + 2] * a; a *= om[4 * q + 2];
;     w[4 * q + 1] = be[4 * q + 1] * a; a *= om[4 * q + 1];
;     w[4 * q + 0] = be[4 * q + 0] * a;
;   }
;   const bf16x8 w0 = cvt8<0>(w), w1 = cvt8<1>(w);
; #pragma unroll
;   for (int d = 0; d < 4; ++d) { O[d] = mfma32(vf[d][0], w0, O[d]); O[d] = mfma32(vf[d][1], w1, O[d]); }
	v_mul_f32_e32 v127, v72, v74
	v_pk_mul_f32 v[106:107], v[92:93], v[92:93] op_sel_hi:[0,1]
	v_mov_b32_e32 v126, v67
	v_add_f32_e32 v66, 1.0, v94
	v_mov_b32_e32 v89, v79
	v_cndmask_b32_e64 v72, 1.0, v121, s[10:11]
	v_mov_b32_e32 v78, v109
	v_mov_b32_e32 v79, v111
	v_mov_b32_e32 v109, v110
	v_pk_mul_f32 v[110:111], v[196:197], v[126:127]
	v_mov_b32_e32 v106, v64
	v_add_f32_e32 v65, 1.0, v169
	v_rcp_f32_e32 v66, v66
	v_mul_f32_e32 v127, v72, v111
	v_pk_mul_f32 v[88:89], v[88:89], v[106:107]
	v_rcp_f32_e32 v65, v65
	v_mul_f32_e32 v126, v105, v127
	ds_bpermute_b32 v105, v170, v89
	v_mov_b32_e32 v95, v120
	v_mov_b32_e32 v120, v66
	v_mul_f32_e32 v73, v73, v126
	v_pk_mul_f32 v[94:95], v[94:95], v[120:121]
	v_mul_f32_e32 v72, v104, v73
	v_mul_f32_e32 v104, v169, v65
	v_pk_mul_f32 v[120:121], v[94:95], v[110:111]
	s_waitcnt lgkmcnt(0)
	v_pk_mul_f32 v[88:89], v[88:89], v[104:105]
	v_cndmask_b32_e64 v90, 1.0, v105, s[10:11]
	v_pk_mul_f32 v[88:89], v[88:89], v[120:121]
	ds_bpermute_b32 v95, v170, v88
	v_cndmask_b32_e64 v74, 1.0, v74, s[10:11]
	v_pk_mul_f32 v[78:79], v[78:79], v[126:127]
	v_pk_mul_f32 v[72:73], v[108:109], v[72:73]
	v_cvt_pk_bf16_f32 v209, v78, v79
	s_waitcnt lgkmcnt(0)
	v_mul_f32_e32 v88, v88, v95
	v_mul_f32_e32 v199, v88, v89
	v_cndmask_b32_e64 v88, 1.0, v95, s[10:11]
	v_mul_f32_e32 v89, v88, v89
	v_mul_f32_e32 v88, v110, v89
	v_pk_mul_f32 v[66:67], v[66:67], v[88:89]
	v_mul_f32_e32 v89, v90, v121
	v_mul_f32_e32 v95, v94, v88
	v_mul_f32_e32 v88, v93, v89
	v_mul_f32_e32 v93, v92, v88
	v_mul_f32_e32 v92, v91, v93
	v_mul_f32_e32 v91, v197, v74
	v_mul_f32_e32 v90, v77, v91
	v_mul_f32_e32 v94, v104, v95
	v_mul_f32_e32 v75, v75, v90
	v_pk_mul_f32 v[64:65], v[64:65], v[94:95]
	v_pk_mul_f32 v[68:69], v[68:69], v[92:93]
	v_pk_mul_f32 v[70:71], v[70:71], v[88:89]
	v_mov_b32_e32 v88, v123
	v_mov_b32_e32 v123, v124
	v_mul_f32_e32 v74, v76, v75
	v_pk_mul_f32 v[74:75], v[122:123], v[74:75]
	v_cvt_pk_bf16_f32 v170, v64, v65
	v_cvt_pk_bf16_f32 v171, v66, v67
	v_cvt_pk_bf16_f32 v172, v68, v69
	v_cvt_pk_bf16_f32 v173, v70, v71
	v_cvt_pk_bf16_f32 v208, v72, v73
	v_cvt_pk_bf16_f32 v210, v74, v75
	v_mfma_f32_32x32x16_bf16 v[64:79], v[84:87], v[170:173], v[48:63]
	v_mov_b32_e32 v89, v125
	v_mul_f32_e64 v88, v88, v90
	v_mul_f32_e64 v89, v89, v91
	v_cvt_pk_bf16_f32 v211, v88, v89
	s_nop 1
	v_mfma_f32_32x32x16_bf16 v[64:79], v[80:83], v[208:211], v[64:79]
	v_mfma_f32_32x32x16_bf16 v[80:95], v[96:99], v[170:173], v[32:47]
	v_mfma_f32_32x32x16_bf16 v[80:95], v[100:103], v[208:211], v[80:95]
	v_mfma_f32_32x32x16_bf16 v[96:111], v[112:115], v[170:173], v[16:31]
	v_mfma_f32_32x32x16_bf16 v[96:111], v[116:119], v[208:211], v[96:111]
	v_mfma_f32_32x32x16_bf16 v[112:127], v[164:167], v[170:173], v[0:15]
	v_mfma_f32_32x32x16_bf16 v[112:127], v[160:163], v[208:211], v[112:127]

; DEV f32x16 mfma32(bf16x8 a, bf16x8 b, f32x16 c) { return __builtin_amdgcn_mfma_f32_32x32x16_bf16(a, b, c, 0, 0, 0); }
; template <bool DIAG>
; DEV void sb_tile(const char* lk, const char* lv, const int ko0, const int vo0, const bf16x8 (&qf)[8], f32x16 (&O)[4], float& accp,
;                  const int l31, const int hh) {
;   f32x16 z;
;   for (int g = 0; g < 16; ++g) z[g] = 0.f;
;   {
;     bf16x8 kf[8];
; #pragma unroll
;     for (int s = 0; s < 8; ++s) kf[s] = *(const bf16x8*)(lk + (ko0 ^ (32 * s)));
;     __builtin_amdgcn_sched_barrier(0);
; #pragma unroll
;     for (int s = 0; s < 8; ++s) z = mfma32(kf[s], qf[s], z);
;   }
;   bf16x8 vf[4][2];
; #pragma unroll
;   for (int d = 0; d < 4; ++d) { vf[d][0] = *(const bf16x8*)(lv + d * 4096 + vo0); vf[d][1] = *(const bf16x8*)(lv + d * 4096 + (vo0 ^ 32)); }
;   __builtin_amdgcn_sched_barrier(0);
;   float be[16], om[16];
; #pragma unroll
;   for (int g = 0; g < 16; ++g) {
;     const float e = __builtin_amdgcn_exp2f(fminf(-z[g], 120.f));
;     be[g] = __builtin_amdgcn_rcpf(1.f + e);
;     om[g] = e * be[g];
;     if (DIAG) { const int kl = (g & 3) + 8 * (g >> 2) + 4 * hh; if (kl >= l31) { be[g] = 0.f; om[g] = 1.f; } }
;   }
;   float gp[4], pp[4], tot[4];
; #pragma unroll
;   for (int q = 0; q < 4; ++q) { gp[q] = (om[4 * q] * om[4 * q + 1]) * (om[4 * q + 2] * om[4 * q + 3]); pp[q] = __shfl_xor(gp[q], 32); tot[q] = gp[q] * pp[q]; }
; DEV void sb_block(const Params& p, int item) {
;     ...
;     if (2 * j + 1 == qt) sb_tile<true>(lb_ + 32 * 256, lb_, ko0, vo0 ^ 64, qf, O, accp, l31, hh);
.LBB0_563:
	v_xor_b32_e32 v160, 0x60, v168
	v_xor_b32_e32 v161, 0x80, v168
	v_xor_b32_e32 v162, 0xa0, v168
	v_xor_b32_e32 v163, 0xc0, v168
	v_xor_b32_e32 v164, 0xe0, v168
	s_andn2_b64 vcc, exec, s[66:67]
	v_add_u32_e32 v195, s92, v168
	v_xad_u32 v196, v168, 32, s92
	v_xad_u32 v207, v168, 64, s92
	v_add_u32_e32 v208, s92, v160
	v_add_u32_e32 v209, s92, v161
	v_add_u32_e32 v210, s92, v162
	v_add_u32_e32 v211, s92, v163
	v_add_u32_e32 v212, s92, v164
	s_cbranch_vccnz .LBB0_565
	ds_read_b128 v[64:67], v195 offset:8192
	ds_read_b128 v[80:83], v196 offset:8192
	ds_read_b128 v[84:87], v207 offset:8192
	ds_read_b128 v[88:91], v208 offset:8192
	ds_read_b128 v[92:95], v209 offset:8192
	ds_read_b128 v[96:99], v210 offset:8192
	ds_read_b128 v[100:103], v211 offset:8192
	ds_read_b128 v[112:115], v212 offset:8192
	s_waitcnt lgkmcnt(0)
	v_mfma_f32_32x32x16_bf16 v[64:79], v[64:67], v[128:131], 0
	v_mfma_f32_32x32x16_bf16 v[64:79], v[80:83], v[132:135], v[64:79]
	v_xor_b32_e32 v80, 0x60, v193
	v_xad_u32 v81, v193, 64, s92
	v_add_u32_e32 v80, s92, v80
	v_mfma_f32_32x32x16_bf16 v[64:79], v[84:87], v[136:139], v[64:79]
	v_mfma_f32_32x32x16_bf16 v[64:79], v[88:91], v[140:143], v[64:79]
	v_mfma_f32_32x32x16_bf16 v[64:79], v[92:95], v[144:147], v[64:79]
	v_mfma_f32_32x32x16_bf16 v[64:79], v[96:99], v[148:151], v[64:79]
	v_mfma_f32_32x32x16_bf16 v[64:79], v[100:103], v[152:155], v[64:79]
	ds_read_b128 v[108:111], v81
	ds_read_b128 v[96:99], v81 offset:4096
	ds_read_b128 v[104:107], v80
	ds_read_b128 v[100:103], v80 offset:4096
	ds_read_b128 v[88:91], v81 offset:8192
	ds_read_b128 v[84:87], v81 offset:12288
	ds_read_b128 v[92:95], v80 offset:8192
	ds_read_b128 v[80:83], v80 offset:12288
	v_mfma_f32_32x32x16_bf16 v[64:79], v[112:115], v[156:159], v[64:79]
	s_nop 11
	v_min_f32_e64 v64, -v64, s32
	v_exp_f32_e32 v64, v64
	v_min_f32_e64 v65, -v65, s32
	v_exp_f32_e32 v65, v65
	v_add_f32_e32 v112, 1.0, v64
	v_rcp_f32_e32 v120, v112
	v_add_f32_e32 v112, 1.0, v65
	v_min_f32_e64 v66, -v66, s32
	v_rcp_f32_e32 v121, v112
	v_exp_f32_e32 v112, v66
	v_min_f32_e64 v66, -v67, s32
	v_exp_f32_e32 v67, v66
	v_add_f32_e32 v66, 1.0, v112
	v_rcp_f32_e32 v122, v66
	v_mul_f32_e32 v65, v65, v121
	v_add_f32_e32 v66, 1.0, v67
	v_rcp_f32_e32 v123, v66
	v_cndmask_b32_e64 v66, 1.0, v65, s[14:15]
	v_mul_f32_e32 v65, v112, v122
	v_cndmask_b32_e64 v112, 1.0, v65, s[16:17]
	v_mul_f32_e32 v65, v67, v123
	v_min_f32_e64 v67, -v68, s32
	v_exp_f32_e32 v67, v67
	v_min_f32_e64 v68, -v69, s32
	v_exp_f32_e32 v69, v68
	v_cndmask_b32_e64 v68, 1.0, v65, s[18:19]
	v_add_f32_e32 v65, 1.0, v67
	v_rcp_f32_e32 v124, v65
	v_add_f32_e32 v65, 1.0, v69
	v_rcp_f32_e32 v125, v65
	v_min_f32_e64 v65, -v70, s32
	v_exp_f32_e32 v65, v65
	v_mul_f32_e32 v67, v67, v124
	v_cndmask_b32_e64 v70, 1.0, v67, s[20:21]
	v_mul_f32_e32 v67, v69, v125
	v_add_f32_e32 v69, 1.0, v65
	v_rcp_f32_e32 v126, v69
	v_min_f32_e64 v69, -v71, s32
	v_exp_f32_e32 v69, v69
	v_mul_f32_e32 v65, v65, v126
	v_cndmask_b32_e64 v115, 1.0, v65, s[24:25]
	v_cndmask_b32_e64 v114, 1.0, v67, s[22:23]
	v_add_f32_e32 v65, 1.0, v69
	v_rcp_f32_e32 v127, v65
	v_min_f32_e64 v65, -v72, s32
	v_exp_f32_e32 v65, v65
	v_min_f32_e64 v67, -v73, s32
	v_exp_f32_e32 v67, v67
	v_mul_f32_e32 v69, v69, v127
	v_add_f32_e32 v71, 1.0, v65
	v_rcp_f32_e32 v160, v71
	v_add_f32_e32 v71, 1.0, v67
	v_rcp_f32_e32 v161, v71
	v_cndmask_b32_e64 v71, 1.0, v69, s[26:27]
	v_mul_f32_e32 v65, v65, v160
	v_cndmask_b32_e64 v72, 1.0, v65, s[28:29]
	v_mul_f32_e32 v65, v67, v161
	v_min_f32_e64 v67, -v74, s32
	v_exp_f32_e32 v67, v67
	v_min_f32_e64 v69, -v75, s32
	v_exp_f32_e32 v69, v69
	v_cndmask_b32_e64 v74, 1.0, v65, s[30:31]
	v_add_f32_e32 v65, 1.0, v67
	v_rcp_f32_e32 v162, v65
	v_add_f32_e32 v65, 1.0, v69
	v_rcp_f32_e32 v163, v65
	v_min_f32_e64 v65, -v76, s32
	v_exp_f32_e32 v65, v65
	v_mul_f32_e32 v67, v67, v162
	v_cndmask_b32_e64 v75, 1.0, v67, s[34:35]
	v_mul_f32_e32 v67, v69, v163
	v_add_f32_e32 v69, 1.0, v65
	v_rcp_f32_e32 v164, v69
	v_min_f32_e64 v69, -v77, s32
	v_exp_f32_e32 v69, v69
	v_mul_f32_e32 v65, v65, v164
	v_cndmask_b32_e64 v76, 1.0, v65, s[38:39]
	v_cndmask_b32_e64 v73, 1.0, v67, s[36:37]
	v_add_f32_e32 v65, 1.0, v69
	v_rcp_f32_e32 v165, v65
	v_min_f32_e64 v65, -v78, s32
	v_exp_f32_e32 v65, v65
	v_min_f32_e64 v67, -v79, s32
	v_exp_f32_e32 v67, v67
	v_mul_f32_e32 v69, v69, v165
	v_add_f32_e32 v77, 1.0, v65
	v_rcp_f32_e32 v166, v77
	v_add_f32_e32 v77, 1.0, v67
	v_rcp_f32_e32 v167, v77
	v_cndmask_b32_e64 v78, 1.0, v69, s[40:41]
	v_mul_f32_e32 v65, v65, v166
	v_cndmask_b32_e64 v79, 1.0, v65, s[42:43]
	v_mul_f32_e32 v65, v67, v167
	v_and_b32_e32 v67, 64, v219
	v_cndmask_b32_e64 v77, 1.0, v65, s[44:45]
	v_xor_b32_e32 v65, 32, v219
	v_add_u32_e32 v67, 64, v67
	v_cmp_lt_i32_e32 vcc, v65, v67
	v_pk_mul_f32 v[116:117], v[74:75], v[72:73]
	v_mul_f32_e32 v64, v64, v120
	v_cndmask_b32_e32 v65, v219, v65, vcc
	v_lshlrev_b32_e32 v168, 2, v65
	v_mul_f32_e32 v65, v116, v117
	v_pk_mul_f32 v[116:117], v[78:79], v[76:77]
	ds_bpermute_b32 v72, v168, v65
	v_mul_f32_e32 v69, v116, v117
	ds_bpermute_b32 v76, v168, v69
	v_pk_mul_f32 v[116:117], v[114:115], v[70:71]
	v_cndmask_b32_e64 v64, 1.0, v64, s[12:13]
	v_pk_mul_f32 v[116:117], v[116:117], v[116:117] op_sel:[0,1] op_sel_hi:[1,0]
	ds_bpermute_b32 v67, v168, v116
	s_waitcnt lgkmcnt(0)
	v_mul_f32_e32 v113, v65, v72
	v_mul_f32_e32 v65, v69, v76
	v_mul_f32_e32 v69, v197, v65
	v_mov_b32_e32 v65, v116
	v_pk_mul_f32 v[64:65], v[64:65], v[66:67]
	v_pk_mul_f32 v[116:117], v[112:113], v[68:69]
	v_cndmask_b32_e64 v113, 1.0, v67, s[10:11]
	v_pk_mul_f32 v[118:119], v[64:65], v[116:117]
	ds_bpermute_b32 v116, v168, v118
	v_cndmask_b32_e64 v67, 1.0, v72, s[10:11]
	v_cndmask_b32_e64 v65, 0, v121, s[14:15]
	v_cndmask_b32_e64 v121, 0, v123, s[18:19]
	v_cndmask_b32_e64 v123, 0, v125, s[22:23]
	s_waitcnt lgkmcnt(0)
; DEV f32x16 mfma32(bf16x8 a, bf16x8 b, f32x16 c) { return __builtin_amdgcn_mfma_f32_32x32x16_bf16(a, b, c, 0, 0, 0); }
; template <bool DIAG>
; DEV void sb_tile(const char* lk, const char* lv, const int ko0, const int vo0, const bf16x8 (&qf)[8], f32x16 (&O)[4], float& accp,
;                  const int l31, const int hh) {
;     ...
;   float suf[4];
;   suf[3] = accp; suf[2] = suf[3] * tot[3]; suf[1] = suf[2] * tot[2]; suf[0] = suf[1] * tot[1];
;   accp = suf[0] * tot[0];
;   f32x16 w;
; #pragma unroll
;   for (int q = 0; q < 4; ++q) {
;     float a = suf[q] * (hh == 0 ? pp[q] : 1.f);
;     w[4 * q + 3] = be[4 * q + 3] * a; a *= om[4 * q + 3];
;     w[4 * q + 2] = be[4 * q + 2] * a; a *= om[4 * q + 2];
;     w[4 * q + 1] = be[4 * q + 1] * a; a *= om[4 * q + 1];
;     w[4 * q + 0] = be[4 * q + 0] * a;
;   }
;   const bf16x8 w0 = cvt8<0>(w), w1 = cvt8<1>(w);
; #pragma unroll
;   for (int d = 0; d < 4; ++d) { O[d] = mfma32(vf[d][0], w0, O[d]); O[d] = mfma32(vf[d][1], w1, O[d]); }
	v_cndmask_b32_e64 v70, 1.0, v116, s[10:11]
	v_cndmask_b32_e64 v125, 0, v127, s[26:27]
	v_cndmask_b32_e64 v127, 0, v161, s[30:31]
	v_cndmask_b32_e64 v161, 0, v163, s[36:37]
	v_cndmask_b32_e64 v163, 0, v165, s[40:41]
	v_cndmask_b32_e64 v165, 0, v167, s[44:45]
	v_mul_f32_e32 v167, v67, v69
	v_mul_f32_e32 v69, v70, v119
	v_mul_f32_e32 v68, v68, v69
	v_mul_f32_e32 v67, v112, v68
	v_cndmask_b32_e64 v64, 0, v120, s[12:13]
	v_cndmask_b32_e64 v120, 0, v122, s[16:17]
	v_mul_f32_e32 v66, v66, v67
	v_pk_mul_f32 v[64:65], v[64:65], v[66:67]
	v_pk_mul_f32 v[66:67], v[120:121], v[68:69]
	v_mul_f32_e32 v69, v113, v117
	v_mul_f32_e32 v68, v71, v69
	v_mul_f32_e32 v71, v115, v68
	v_cndmask_b32_e64 v122, 0, v124, s[20:21]
	v_cndmask_b32_e64 v124, 0, v126, s[24:25]
	v_mul_f32_e32 v70, v114, v71
	v_pk_mul_f32 v[70:71], v[122:123], v[70:71]
	v_pk_mul_f32 v[68:69], v[124:125], v[68:69]
	v_cvt_pk_bf16_f32 v64, v64, v65
	v_cvt_pk_bf16_f32 v65, v66, v67
	v_cvt_pk_bf16_f32 v66, v70, v71
	v_cvt_pk_bf16_f32 v67, v68, v69
	v_cndmask_b32_e64 v76, 1.0, v76, s[10:11]
	v_mul_f32_e32 v113, v197, v76
	v_mfma_f32_32x32x16_bf16 v[48:63], v[108:111], v[64:67], v[48:63]
	v_cndmask_b32_e64 v126, 0, v160, s[28:29]
	v_cndmask_b32_e64 v160, 0, v162, s[34:35]
	v_cndmask_b32_e64 v162, 0, v164, s[38:39]
	v_cndmask_b32_e64 v164, 0, v166, s[42:43]
	v_mul_f32_e32 v166, v73, v167
	v_mul_f32_e32 v112, v113, v77
	v_mul_f32_e32 v75, v75, v166
	v_mfma_f32_32x32x16_bf16 v[32:47], v[96:99], v[64:67], v[32:47]
	v_mul_f32_e32 v69, v79, v112
	v_mul_f32_e32 v74, v74, v75
	v_mul_f32_e32 v68, v78, v69
	v_mul_f32_e64 v72, v160, v166
	v_mul_f32_e64 v73, v161, v167
	v_pk_mul_f32 v[74:75], v[126:127], v[74:75]
	v_pk_mul_f32 v[76:77], v[164:165], v[112:113]
	v_pk_mul_f32 v[70:71], v[162:163], v[68:69]
	v_mfma_f32_32x32x16_bf16 v[16:31], v[88:91], v[64:67], v[16:31]
	v_cvt_pk_bf16_f32 v68, v74, v75
	v_cvt_pk_bf16_f32 v69, v72, v73
	v_cvt_pk_bf16_f32 v70, v70, v71
	v_cvt_pk_bf16_f32 v71, v76, v77
	v_mfma_f32_32x32x16_bf16 v[0:15], v[84:87], v[64:67], v[0:15]
	v_mul_f32_e32 v64, v118, v116
	v_mul_f32_e32 v199, v64, v119
	v_mfma_f32_32x32x16_bf16 v[48:63], v[104:107], v[68:71], v[48:63]
	v_mfma_f32_32x32x16_bf16 v[32:47], v[100:103], v[68:71], v[32:47]
	v_mfma_f32_32x32x16_bf16 v[16:31], v[92:95], v[68:71], v[16:31]
	v_mfma_f32_32x32x16_bf16 v[0:15], v[80:83], v[68:71], v[0:15]
	s_nop 10
	v_mov_b64_e32 v[110:111], v[30:31]
	v_mov_b64_e32 v[94:95], v[46:47]
	v_mov_b64_e32 v[78:79], v[62:63]
	v_mov_b64_e32 v[108:109], v[28:29]
	v_mov_b64_e32 v[106:107], v[26:27]
	v_mov_b64_e32 v[104:105], v[24:25]
	v_mov_b64_e32 v[102:103], v[22:23]
	v_mov_b64_e32 v[126:127], v[14:15]
	v_mov_b64_e32 v[124:125], v[12:13]
	v_mov_b64_e32 v[122:123], v[10:11]
	v_mov_b64_e32 v[120:121], v[8:9]
	v_mov_b64_e32 v[118:119], v[6:7]
	v_mov_b64_e32 v[116:117], v[4:5]
	v_mov_b64_e32 v[114:115], v[2:3]
	v_mov_b64_e32 v[112:113], v[0:1]
	v_mov_b64_e32 v[100:101], v[20:21]
	v_mov_b64_e32 v[98:99], v[18:19]
	v_mov_b64_e32 v[96:97], v[16:17]
	v_mov_b64_e32 v[92:93], v[44:45]
	v_mov_b64_e32 v[90:91], v[42:43]
	v_mov_b64_e32 v[88:89], v[40:41]
	v_mov_b64_e32 v[86:87], v[38:39]
	v_mov_b64_e32 v[84:85], v[36:37]
	v_mov_b64_e32 v[82:83], v[34:35]
	v_mov_b64_e32 v[80:81], v[32:33]
	v_mov_b64_e32 v[76:77], v[60:61]
	v_mov_b64_e32 v[74:75], v[58:59]
	v_mov_b64_e32 v[72:73], v[56:57]
	v_mov_b64_e32 v[70:71], v[54:55]
	v_mov_b64_e32 v[68:69], v[52:53]
	v_mov_b64_e32 v[66:67], v[50:51]
	v_mov_b64_e32 v[64:65], v[48:49]
; DEV f32x16 mfma32(bf16x8 a, bf16x8 b, f32x16 c) { return __builtin_amdgcn_mfma_f32_32x32x16_bf16(a, b, c, 0, 0, 0); }
; template <bool DIAG>
; DEV void sb_tile(const char* lk, const char* lv, const int ko0, const int vo0, const bf16x8 (&qf)[8], f32x16 (&O)[4], float& accp,
;                  const int l31, const int hh) {
;   f32x16 z;
;   for (int g = 0; g < 16; ++g) z[g] = 0.f;
;   {
;     bf16x8 kf[8];
; #pragma unroll
;     for (int s = 0; s < 8; ++s) kf[s] = *(const bf16x8*)(lk + (ko0 ^ (32 * s)));
;     __builtin_amdgcn_sched_barrier(0);
; #pragma unroll
;     for (int s = 0; s < 8; ++s) z = mfma32(kf[s], qf[s], z);
;   }
;   bf16x8 vf[4][2];
; #pragma unroll
;   for (int d = 0; d < 4; ++d) { vf[d][0] = *(const bf16x8*)(lv + d * 4096 + vo0); vf[d][1] = *(const bf16x8*)(lv + d * 4096 + (vo0 ^ 32)); }
;   __builtin_amdgcn_sched_barrier(0);
;   float be[16], om[16];
; #pragma unroll
;   for (int g = 0; g < 16; ++g) {
;     const float e = __builtin_amdgcn_exp2f(fminf(-z[g], 120.f));
;     be[g] = __builtin_amdgcn_rcpf(1.f + e);
;     om[g] = e * be[g];
;     if (DIAG) { const int kl = (g & 3) + 8 * (g >> 2) + 4 * hh; if (kl >= l31) { be[g] = 0.f; om[g] = 1.f; } }
;   }
;   float gp[4], pp[4], tot[4];
; #pragma unroll
;   for (int q = 0; q < 4; ++q) { gp[q] = (om[4 * q] * om[4 * q + 1]) * (om[4 * q + 2] * om[4 * q + 3]); pp[q] = __shfl_xor(gp[q], 32); tot[q] = gp[q] * pp[q]; }
;   float suf[4];
;   suf[3] = accp; suf[2] = suf[3] * tot[3]; suf[1] = suf[2] * tot[2]; suf[0] = suf[1] * tot[1];
;   accp = suf[0] * tot[0];
;   f32x16 w;
; #pragma unroll
;   for (int q = 0; q < 4; ++q) {
;     float a = suf[q] * (hh == 0 ? pp[q] : 1.f);
;     w[4 * q + 3] = be[4 * q + 3] * a; a *= om[4 * q + 3];
;     w[4 * q + 2] = be[4 * q + 2] * a; a *= om[4 * q + 2];
;     w[4 * q + 1] = be[4 * q + 1] * a; a *= om[4 * q + 1];
;     w[4 * q + 0] = be[4 * q + 0] * a;
;   }
;   const bf16x8 w0 = cvt8<0>(w), w1 = cvt8<1>(w);
; #pragma unroll
;   for (int d = 0; d < 4; ++d) { O[d] = mfma32(vf[d][0], w0, O[d]); O[d] = mfma32(vf[d][1], w1, O[d]); }
; DEV void sb_block(const Params& p, int item) {
;     ...
;     if (2 * j == qt) sb_tile<true>(lb_, lb_, ko0, vo0, qf, O, accp, l31, hh);
;     else if (2 * j < qt) sb_tile<false>(lb_, lb_, ko0, vo0, qf, O, accp, l31, hh);
.LBB0_565:
	s_cmp_lg_u32 s88, s69
	s_mov_b64 s[66:67], -1
	s_cbranch_scc0 .LBB0_569
	s_add_i32 s0, s0, 6
	s_cmp_ge_i32 s0, s75
	s_cbranch_scc1 .Lsb_skip_B0
	ds_read_b128 v[0:3], v195
	ds_read_b128 v[16:19], v196
	ds_read_b128 v[20:23], v207
	ds_read_b128 v[24:27], v208
	ds_read_b128 v[28:31], v209
	ds_read_b128 v[32:35], v210
	ds_read_b128 v[36:39], v211
	ds_read_b128 v[40:43], v212
	s_waitcnt lgkmcnt(0)
	v_mfma_f32_32x32x16_bf16 v[0:15], v[0:3], v[128:131], 0
	v_mfma_f32_32x32x16_bf16 v[0:15], v[16:19], v[132:135], v[0:15]
	v_mfma_f32_32x32x16_bf16 v[0:15], v[20:23], v[136:139], v[0:15]
	v_mfma_f32_32x32x16_bf16 v[0:15], v[24:27], v[140:143], v[0:15]
	v_mfma_f32_32x32x16_bf16 v[0:15], v[28:31], v[144:147], v[0:15]
	v_mfma_f32_32x32x16_bf16 v[0:15], v[32:35], v[148:151], v[0:15]
	v_add_u32_e32 v32, s92, v193
	v_xad_u32 v33, v193, 32, s92
	ds_read_b128 v[28:31], v32
	ds_read_b128 v[16:19], v32 offset:4096
	ds_read_b128 v[24:27], v33
	ds_read_b128 v[20:23], v33 offset:4096
	ds_read_b128 v[168:171], v32 offset:8192
	ds_read_b128 v[164:167], v32 offset:12288
	ds_read_b128 v[172:175], v33 offset:8192
	ds_read_b128 v[160:163], v33 offset:12288
	v_mfma_f32_32x32x16_bf16 v[0:15], v[36:39], v[152:155], v[0:15]
	v_mfma_f32_32x32x16_bf16 v[0:15], v[40:43], v[156:159], v[0:15]
	s_nop 11
	v_min_f32_e64 v4, -v4, s32
	v_exp_f32_e32 v34, v4
	v_min_f32_e64 v4, -v5, s32
	v_exp_f32_e32 v35, v4
	v_add_f32_e32 v4, 1.0, v34
	v_min_f32_e64 v9, -v9, s32
	v_add_f32_e32 v5, 1.0, v35
	v_rcp_f32_e32 v4, v4
	v_rcp_f32_e32 v5, v5
	v_exp_f32_e32 v40, v9
	v_max_f32_e64 v9, -v10, -v10
	v_max_f32_e64 v10, -v11, -v11
	v_min_f32_e64 v8, -v8, s32
	v_min_f32_e32 v10, 0x42f00000, v10
	v_min_f32_e64 v11, -v13, s32
	v_max_f32_e64 v13, -v15, -v15
	v_and_b32_e32 v15, 64, v219
	v_exp_f32_e32 v8, v8
	v_exp_f32_e32 v41, v10
	v_max_f32_e64 v10, -v12, -v12
	v_exp_f32_e32 v12, v11
	v_max_f32_e64 v11, -v14, -v14
	v_xor_b32_e32 v14, 32, v219
	v_add_u32_e32 v15, 64, v15
	v_min_f32_e32 v9, 0x42f00000, v9
	v_cmp_lt_i32_e32 vcc, v14, v15
	v_pk_mul_f32 v[34:35], v[34:35], v[4:5]
	v_exp_f32_e32 v9, v9
	v_cndmask_b32_e32 v14, v219, v14, vcc
	v_lshlrev_b32_e32 v57, 2, v14
	v_pk_mul_f32 v[14:15], v[34:35], v[34:35] op_sel_hi:[0,1]
	v_add_f32_e32 v14, 1.0, v8
	v_rcp_f32_e32 v44, v14
	v_add_f32_e32 v14, 1.0, v40
	v_rcp_f32_e32 v46, v14
	v_add_f32_e32 v14, 1.0, v9
	v_rcp_f32_e32 v45, v14
	v_add_f32_e32 v14, 1.0, v41
	v_min_f32_e32 v10, 0x42f00000, v10
	v_rcp_f32_e32 v47, v14
	v_exp_f32_e32 v10, v10
	v_min_f32_e32 v11, 0x42f00000, v11
	v_exp_f32_e32 v11, v11
	v_min_f32_e32 v13, 0x42f00000, v13
	v_exp_f32_e32 v13, v13
	v_pk_mul_f32 v[8:9], v[8:9], v[44:45]
	v_pk_mul_f32 v[40:41], v[40:41], v[46:47]
	v_pk_mul_f32 v[48:49], v[8:9], v[40:41]
	v_add_f32_e32 v8, 1.0, v10
	v_rcp_f32_e32 v50, v8
	v_add_f32_e32 v8, 1.0, v12
	v_rcp_f32_e32 v52, v8
	v_add_f32_e32 v8, 1.0, v11
	v_min_f32_e64 v6, -v6, s32
	v_rcp_f32_e32 v51, v8
	v_add_f32_e32 v8, 1.0, v13
	v_exp_f32_e32 v36, v6
	v_rcp_f32_e32 v53, v8
	v_min_f32_e64 v6, -v7, s32
	v_min_f32_e64 v3, -v3, s32
	v_exp_f32_e32 v37, v6
	v_min_f32_e64 v0, -v0, s32
	v_exp_f32_e32 v198, v3
	v_exp_f32_e32 v32, v0
	v_pk_mul_f32 v[10:11], v[10:11], v[50:51]
	v_pk_mul_f32 v[12:13], v[12:13], v[52:53]
	v_add_f32_e32 v6, 1.0, v36
	v_pk_mul_f32 v[54:55], v[10:11], v[12:13]
	v_add_f32_e32 v7, 1.0, v37
	v_mul_f32_e32 v8, v54, v55
	v_add_f32_e32 v3, 1.0, v198
	v_rcp_f32_e32 v6, v6
	v_rcp_f32_e32 v7, v7
	v_pk_mul_f32 v[48:49], v[48:49], v[48:49] op_sel:[0,1] op_sel_hi:[1,0]
	ds_bpermute_b32 v10, v57, v8
	v_add_f32_e32 v0, 1.0, v32
	v_min_f32_e64 v2, -v2, s32
	v_rcp_f32_e32 v3, v3
	ds_bpermute_b32 v49, v57, v48
	v_rcp_f32_e32 v0, v0
	v_min_f32_e64 v1, -v1, s32
	v_exp_f32_e32 v38, v2
	v_exp_f32_e32 v56, v1
	v_pk_mul_f32 v[36:37], v[36:37], v[6:7]
	s_waitcnt lgkmcnt(0)
	v_mul_f32_e32 v55, v8, v10
	v_pk_mul_f32 v[42:43], v[36:37], v[36:37] op_sel_hi:[0,1]
	v_mov_b32_e32 v54, v3
	v_add_f32_e32 v2, 1.0, v38
	v_mov_b32_e32 v33, v15
	v_cndmask_b32_e64 v8, 1.0, v49, s[10:11]
	v_mov_b32_e32 v14, v45
	v_mov_b32_e32 v15, v47
	v_mov_b32_e32 v45, v46
	v_pk_mul_f32 v[46:47], v[198:199], v[54:55]
	v_mov_b32_e32 v42, v0
	v_add_f32_e32 v1, 1.0, v56
	v_rcp_f32_e32 v2, v2
	v_mul_f32_e32 v55, v8, v47
	v_pk_mul_f32 v[32:33], v[32:33], v[42:43]
	v_rcp_f32_e32 v1, v1
	v_mul_f32_e32 v54, v41, v55
	ds_bpermute_b32 v41, v57, v33
	v_mov_b32_e32 v39, v48
	v_mov_b32_e32 v48, v2
	v_mul_f32_e32 v9, v9, v54
	v_pk_mul_f32 v[38:39], v[38:39], v[48:49]
	v_mul_f32_e32 v8, v40, v9
	v_mul_f32_e32 v40, v56, v1
	v_pk_mul_f32 v[48:49], v[38:39], v[46:47]
	s_waitcnt lgkmcnt(0)
	v_pk_mul_f32 v[32:33], v[32:33], v[40:41]
	v_cndmask_b32_e64 v34, 1.0, v41, s[10:11]
	v_pk_mul_f32 v[32:33], v[32:33], v[48:49]
	ds_bpermute_b32 v39, v57, v32
	v_cndmask_b32_e64 v10, 1.0, v10, s[10:11]
	v_pk_mul_f32 v[14:15], v[14:15], v[54:55]
	v_pk_mul_f32 v[8:9], v[44:45], v[8:9]
	v_cvt_pk_bf16_f32 v225, v14, v15
	s_waitcnt lgkmcnt(0)
	v_mul_f32_e32 v32, v32, v39
	v_mul_f32_e32 v197, v32, v33
	v_cndmask_b32_e64 v32, 1.0, v39, s[10:11]
	v_mul_f32_e32 v33, v32, v33
	v_mul_f32_e32 v32, v46, v33
	v_pk_mul_f32 v[2:3], v[2:3], v[32:33]
	v_mul_f32_e32 v33, v34, v49
	v_mul_f32_e32 v39, v38, v32
	v_mul_f32_e32 v32, v37, v33
	v_mul_f32_e32 v37, v36, v32
	v_mul_f32_e32 v36, v35, v37
	v_mul_f32_e32 v35, v199, v10
	v_mul_f32_e32 v38, v40, v39
	v_mul_f32_e32 v34, v13, v35
	v_pk_mul_f32 v[0:1], v[0:1], v[38:39]
	v_pk_mul_f32 v[4:5], v[4:5], v[36:37]
	v_pk_mul_f32 v[6:7], v[6:7], v[32:33]
	v_mov_b32_e32 v32, v51
	v_mov_b32_e32 v33, v53
	v_mul_f32_e32 v11, v11, v34
	v_pk_mul_f32 v[32:33], v[32:33], v[34:35]
	v_mov_b32_e32 v51, v52
	v_mul_f32_e32 v10, v12, v11
	v_cvt_pk_bf16_f32 v214, v0, v1
	v_cvt_pk_bf16_f32 v215, v2, v3
	v_cvt_pk_bf16_f32 v216, v4, v5
	v_cvt_pk_bf16_f32 v217, v6, v7
	v_pk_mul_f32 v[10:11], v[50:51], v[10:11]
	v_cvt_pk_bf16_f32 v227, v32, v33
	v_mfma_f32_32x32x16_bf16 v[48:63], v[28:31], v[214:217], v[64:79]
	v_cvt_pk_bf16_f32 v224, v8, v9
	v_cvt_pk_bf16_f32 v226, v10, v11
	v_mfma_f32_32x32x16_bf16 v[32:47], v[16:19], v[214:217], v[80:95]
	s_nop 0
	v_mfma_f32_32x32x16_bf16 v[48:63], v[24:27], v[224:227], v[48:63]
	v_mfma_f32_32x32x16_bf16 v[32:47], v[20:23], v[224:227], v[32:47]
	v_mfma_f32_32x32x16_bf16 v[16:31], v[168:171], v[214:217], v[96:111]
	v_mfma_f32_32x32x16_bf16 v[0:15], v[164:167], v[214:217], v[112:127]
	v_mfma_f32_32x32x16_bf16 v[16:31], v[172:175], v[224:227], v[16:31]
	v_mfma_f32_32x32x16_bf16 v[0:15], v[160:163], v[224:227], v[0:15]

; DEV f32x16 mfma32(bf16x8 a, bf16x8 b, f32x16 c) { return __builtin_amdgcn_mfma_f32_32x32x16_bf16(a, b, c, 0, 0, 0); }
; template <bool DIAG>
; DEV void sb_tile(const char* lk, const char* lv, const int ko0, const int vo0, const bf16x8 (&qf)[8], f32x16 (&O)[4], float& accp,
;                  const int l31, const int hh) {
;   f32x16 z;
;   for (int g = 0; g < 16; ++g) z[g] = 0.f;
;   {
;     bf16x8 kf[8];
; #pragma unroll
;     for (int s = 0; s < 8; ++s) kf[s] = *(const bf16x8*)(lk + (ko0 ^ (32 * s)));
;     __builtin_amdgcn_sched_barrier(0);
; #pragma unroll
;     for (int s = 0; s < 8; ++s) z = mfma32(kf[s], qf[s], z);
;   }
;   bf16x8 vf[4][2];
; #pragma unroll
;   for (int d = 0; d < 4; ++d) { vf[d][0] = *(const bf16x8*)(lv + d * 4096 + vo0); vf[d][1] = *(const bf16x8*)(lv + d * 4096 + (vo0 ^ 32)); }
;   __builtin_amdgcn_sched_barrier(0);
;   float be[16], om[16];
; #pragma unroll
;   for (int g = 0; g < 16; ++g) {
;     const float e = __builtin_amdgcn_exp2f(fminf(-z[g], 120.f));
;     be[g] = __builtin_amdgcn_rcpf(1.f + e);
;     om[g] = e * be[g];
;     if (DIAG) { const int kl = (g & 3) + 8 * (g >> 2) + 4 * hh; if (kl >= l31) { be[g] = 0.f; om[g] = 1.f; } }
;   }
;   float gp[4], pp[4], tot[4];
; #pragma unroll
;   for (int q = 0; q < 4; ++q) { gp[q] = (om[4 * q] * om[4 * q + 1]) * (om[4 * q + 2] * om[4 * q + 3]); pp[q] = __shfl_xor(gp[q], 32); tot[q] = gp[q] * pp[q]; }
; DEV void sb_block(const Params& p, int item) {
;     ...
;     if (2 * j == qt) sb_tile<true>(lb_, lb_, ko0, vo0, qf, O, accp, l31, hh);
.LBB0_570:
	s_nop 9
	ds_read_b128 v[0:3], v195
	ds_read_b128 v[16:19], v196
	ds_read_b128 v[20:23], v207
	ds_read_b128 v[24:27], v208
	ds_read_b128 v[28:31], v209
	ds_read_b128 v[32:35], v210
	ds_read_b128 v[36:39], v211
	ds_read_b128 v[48:51], v212
	s_waitcnt lgkmcnt(0)
	v_mfma_f32_32x32x16_bf16 v[0:15], v[0:3], v[128:131], 0
	v_mfma_f32_32x32x16_bf16 v[0:15], v[16:19], v[132:135], v[0:15]
	v_add_u32_e32 v16, s92, v193
	v_xad_u32 v17, v193, 32, s92
	v_mfma_f32_32x32x16_bf16 v[0:15], v[20:23], v[136:139], v[0:15]
	v_mfma_f32_32x32x16_bf16 v[0:15], v[24:27], v[140:143], v[0:15]
	v_mfma_f32_32x32x16_bf16 v[0:15], v[28:31], v[144:147], v[0:15]
	v_mfma_f32_32x32x16_bf16 v[0:15], v[32:35], v[148:151], v[0:15]
	v_mfma_f32_32x32x16_bf16 v[0:15], v[36:39], v[152:155], v[0:15]
	ds_read_b128 v[44:47], v16
	ds_read_b128 v[32:35], v16 offset:4096
	ds_read_b128 v[40:43], v17
	ds_read_b128 v[36:39], v17 offset:4096
	ds_read_b128 v[24:27], v16 offset:8192
	ds_read_b128 v[20:23], v16 offset:12288
	ds_read_b128 v[28:31], v17 offset:8192
	ds_read_b128 v[16:19], v17 offset:12288
	v_mfma_f32_32x32x16_bf16 v[0:15], v[48:51], v[156:159], v[0:15]
	s_nop 11
	v_min_f32_e64 v0, -v0, s32
	v_exp_f32_e32 v0, v0
	v_min_f32_e64 v1, -v1, s32
	v_exp_f32_e32 v1, v1
	v_add_f32_e32 v48, 1.0, v0
	v_rcp_f32_e32 v56, v48
	v_add_f32_e32 v48, 1.0, v1
	v_min_f32_e64 v2, -v2, s32
	v_rcp_f32_e32 v57, v48
	v_exp_f32_e32 v48, v2
	v_min_f32_e64 v2, -v3, s32
	v_exp_f32_e32 v3, v2
	v_add_f32_e32 v2, 1.0, v48
	v_rcp_f32_e32 v58, v2
	v_mul_f32_e32 v1, v1, v57
	v_add_f32_e32 v2, 1.0, v3
	v_rcp_f32_e32 v59, v2
	v_cndmask_b32_e64 v2, 1.0, v1, s[14:15]
	v_mul_f32_e32 v1, v48, v58
	v_cndmask_b32_e64 v48, 1.0, v1, s[16:17]
	v_mul_f32_e32 v1, v3, v59
	v_min_f32_e64 v3, -v4, s32
	v_exp_f32_e32 v3, v3
	v_min_f32_e64 v4, -v5, s32
	v_exp_f32_e32 v5, v4
	v_cndmask_b32_e64 v4, 1.0, v1, s[18:19]
	v_add_f32_e32 v1, 1.0, v3
	v_rcp_f32_e32 v60, v1
	v_add_f32_e32 v1, 1.0, v5
	v_rcp_f32_e32 v61, v1
	v_min_f32_e64 v1, -v6, s32
	v_exp_f32_e32 v1, v1
	v_mul_f32_e32 v3, v3, v60
	v_cndmask_b32_e64 v6, 1.0, v3, s[20:21]
	v_mul_f32_e32 v3, v5, v61
	v_add_f32_e32 v5, 1.0, v1
	v_rcp_f32_e32 v62, v5
	v_min_f32_e64 v5, -v7, s32
	v_exp_f32_e32 v5, v5
	v_mul_f32_e32 v1, v1, v62
	v_cndmask_b32_e64 v51, 1.0, v1, s[24:25]
	v_cndmask_b32_e64 v50, 1.0, v3, s[22:23]
	v_add_f32_e32 v1, 1.0, v5
	v_rcp_f32_e32 v63, v1
	v_min_f32_e64 v1, -v8, s32
	v_exp_f32_e32 v1, v1
	v_min_f32_e64 v3, -v9, s32
	v_exp_f32_e32 v3, v3
	v_mul_f32_e32 v5, v5, v63
	v_add_f32_e32 v7, 1.0, v1
	v_rcp_f32_e32 v160, v7
	v_add_f32_e32 v7, 1.0, v3
	v_rcp_f32_e32 v161, v7
	v_cndmask_b32_e64 v7, 1.0, v5, s[26:27]
	v_mul_f32_e32 v1, v1, v160
	v_cndmask_b32_e64 v8, 1.0, v1, s[28:29]
	v_mul_f32_e32 v1, v3, v161
	v_min_f32_e64 v3, -v10, s32
	v_exp_f32_e32 v3, v3
	v_min_f32_e64 v5, -v11, s32
	v_exp_f32_e32 v5, v5
	v_cndmask_b32_e64 v10, 1.0, v1, s[30:31]
	v_add_f32_e32 v1, 1.0, v3
	v_rcp_f32_e32 v162, v1
	v_add_f32_e32 v1, 1.0, v5
	v_rcp_f32_e32 v163, v1
	v_min_f32_e64 v1, -v12, s32
	v_exp_f32_e32 v1, v1
	v_mul_f32_e32 v3, v3, v162
	v_cndmask_b32_e64 v11, 1.0, v3, s[34:35]
	v_mul_f32_e32 v3, v5, v163
	v_add_f32_e32 v5, 1.0, v1
	v_rcp_f32_e32 v164, v5
	v_min_f32_e64 v5, -v13, s32
	v_exp_f32_e32 v5, v5
	v_mul_f32_e32 v1, v1, v164
	v_cndmask_b32_e64 v12, 1.0, v1, s[38:39]
	v_cndmask_b32_e64 v9, 1.0, v3, s[36:37]
	v_add_f32_e32 v1, 1.0, v5
	v_rcp_f32_e32 v165, v1
	v_min_f32_e64 v1, -v14, s32
	v_exp_f32_e32 v1, v1
	v_min_f32_e64 v3, -v15, s32
	v_exp_f32_e32 v3, v3
	v_mul_f32_e32 v5, v5, v165
	v_add_f32_e32 v13, 1.0, v1
	v_rcp_f32_e32 v166, v13
	v_add_f32_e32 v13, 1.0, v3
	v_rcp_f32_e32 v167, v13
	v_cndmask_b32_e64 v14, 1.0, v5, s[40:41]
	v_mul_f32_e32 v1, v1, v166
	v_cndmask_b32_e64 v15, 1.0, v1, s[42:43]
	v_mul_f32_e32 v1, v3, v167
	v_and_b32_e32 v3, 64, v219
	v_cndmask_b32_e64 v13, 1.0, v1, s[44:45]
	v_xor_b32_e32 v1, 32, v219
	v_add_u32_e32 v3, 64, v3
	v_cmp_lt_i32_e32 vcc, v1, v3
	v_pk_mul_f32 v[52:53], v[10:11], v[8:9]
	v_mul_f32_e32 v0, v0, v56
	v_cndmask_b32_e32 v1, v219, v1, vcc
	v_lshlrev_b32_e32 v168, 2, v1
	v_mul_f32_e32 v1, v52, v53
	v_pk_mul_f32 v[52:53], v[14:15], v[12:13]
	ds_bpermute_b32 v8, v168, v1
	v_mul_f32_e32 v5, v52, v53
	ds_bpermute_b32 v12, v168, v5
	v_pk_mul_f32 v[52:53], v[50:51], v[6:7]
	v_cndmask_b32_e64 v0, 1.0, v0, s[12:13]
	v_pk_mul_f32 v[52:53], v[52:53], v[52:53] op_sel:[0,1] op_sel_hi:[1,0]
	ds_bpermute_b32 v3, v168, v52
	s_waitcnt lgkmcnt(0)
	v_mul_f32_e32 v49, v1, v8
	v_mul_f32_e32 v1, v5, v12
	v_mul_f32_e32 v5, v199, v1
	v_mov_b32_e32 v1, v52
	v_pk_mul_f32 v[0:1], v[0:1], v[2:3]
	v_pk_mul_f32 v[52:53], v[48:49], v[4:5]
	v_cndmask_b32_e64 v49, 1.0, v3, s[10:11]
	v_pk_mul_f32 v[54:55], v[0:1], v[52:53]
	ds_bpermute_b32 v52, v168, v54
	v_cndmask_b32_e64 v3, 1.0, v8, s[10:11]
	v_cndmask_b32_e64 v1, 0, v57, s[14:15]
	v_cndmask_b32_e64 v57, 0, v59, s[18:19]
	v_cndmask_b32_e64 v59, 0, v61, s[22:23]
	s_waitcnt lgkmcnt(0)
; DEV f32x16 mfma32(bf16x8 a, bf16x8 b, f32x16 c) { return __builtin_amdgcn_mfma_f32_32x32x16_bf16(a, b, c, 0, 0, 0); }
; template <bool DIAG>
; DEV void sb_tile(const char* lk, const char* lv, const int ko0, const int vo0, const bf16x8 (&qf)[8], f32x16 (&O)[4], float& accp,
;                  const int l31, const int hh) {
;     ...
;   float suf[4];
;   suf[3] = accp; suf[2] = suf[3] * tot[3]; suf[1] = suf[2] * tot[2]; suf[0] = suf[1] * tot[1];
;   accp = suf[0] * tot[0];
;   f32x16 w;
; #pragma unroll
;   for (int q = 0; q < 4; ++q) {
;     float a = suf[q] * (hh == 0 ? pp[q] : 1.f);
;     w[4 * q + 3] = be[4 * q + 3] * a; a *= om[4 * q + 3];
;     w[4 * q + 2] = be[4 * q + 2] * a; a *= om[4 * q + 2];
;     w[4 * q + 1] = be[4 * q + 1] * a; a *= om[4 * q + 1];
;     w[4 * q + 0] = be[4 * q + 0] * a;
;   }
;   const bf16x8 w0 = cvt8<0>(w), w1 = cvt8<1>(w);
; #pragma unroll
;   for (int d = 0; d < 4; ++d) { O[d] = mfma32(vf[d][0], w0, O[d]); O[d] = mfma32(vf[d][1], w1, O[d]); }
; DEV void sb_block(const Params& p, int item) {
;     ...
;     if (2 * j + 1 == qt) sb_tile<true>(lb_ + 32 * 256, lb_, ko0, vo0 ^ 64, qf, O, accp, l31, hh);
;     else if (2 * j + 1 < qt) sb_tile<false>(lb_ + 32 * 256, lb_, ko0, vo0 ^ 64, qf, O, accp, l31, hh);
;     if (2 * j == qt) sb_tile<true>(lb_, lb_, ko0, vo0, qf, O, accp, l31, hh);
;     else if (2 * j < qt) sb_tile<false>(lb_, lb_, ko0, vo0, qf, O, accp, l31, hh);
	v_cndmask_b32_e64 v6, 1.0, v52, s[10:11]
	v_cndmask_b32_e64 v61, 0, v63, s[26:27]
	v_cndmask_b32_e64 v63, 0, v161, s[30:31]
	v_cndmask_b32_e64 v161, 0, v163, s[36:37]
	v_cndmask_b32_e64 v163, 0, v165, s[40:41]
	v_cndmask_b32_e64 v165, 0, v167, s[44:45]
	v_mul_f32_e32 v167, v3, v5
	v_mul_f32_e32 v5, v6, v55
	v_mul_f32_e32 v4, v4, v5
	v_mul_f32_e32 v3, v48, v4
	v_cndmask_b32_e64 v0, 0, v56, s[12:13]
	v_cndmask_b32_e64 v56, 0, v58, s[16:17]
	v_mul_f32_e32 v2, v2, v3
	v_pk_mul_f32 v[0:1], v[0:1], v[2:3]
	v_pk_mul_f32 v[2:3], v[56:57], v[4:5]
	v_mul_f32_e32 v5, v49, v53
	v_mul_f32_e32 v4, v7, v5
	v_mul_f32_e32 v7, v51, v4
	v_cndmask_b32_e64 v58, 0, v60, s[20:21]
	v_cndmask_b32_e64 v60, 0, v62, s[24:25]
	v_mul_f32_e32 v6, v50, v7
	v_pk_mul_f32 v[6:7], v[58:59], v[6:7]
	v_pk_mul_f32 v[4:5], v[60:61], v[4:5]
	v_cvt_pk_bf16_f32 v0, v0, v1
	v_cvt_pk_bf16_f32 v1, v2, v3
	v_cvt_pk_bf16_f32 v2, v6, v7
	v_cvt_pk_bf16_f32 v3, v4, v5
	v_cndmask_b32_e64 v12, 1.0, v12, s[10:11]
	v_mul_f32_e32 v49, v199, v12
	v_mfma_f32_32x32x16_bf16 v[64:79], v[44:47], v[0:3], v[64:79]
	v_cndmask_b32_e64 v62, 0, v160, s[28:29]
	v_cndmask_b32_e64 v160, 0, v162, s[34:35]
	v_cndmask_b32_e64 v162, 0, v164, s[38:39]
	v_cndmask_b32_e64 v164, 0, v166, s[42:43]
	v_mul_f32_e32 v166, v9, v167
	v_mul_f32_e32 v48, v49, v13
	v_mul_f32_e32 v11, v11, v166
	v_mfma_f32_32x32x16_bf16 v[80:95], v[32:35], v[0:3], v[80:95]
	v_mul_f32_e32 v5, v15, v48
	v_mul_f32_e32 v10, v10, v11
	v_mul_f32_e32 v4, v14, v5
	v_mul_f32_e64 v8, v160, v166
	v_mul_f32_e64 v9, v161, v167
	v_pk_mul_f32 v[10:11], v[62:63], v[10:11]
	v_pk_mul_f32 v[12:13], v[164:165], v[48:49]
	v_pk_mul_f32 v[6:7], v[162:163], v[4:5]
	v_mfma_f32_32x32x16_bf16 v[96:111], v[24:27], v[0:3], v[96:111]
	v_cvt_pk_bf16_f32 v4, v10, v11
	v_cvt_pk_bf16_f32 v5, v8, v9
	v_cvt_pk_bf16_f32 v6, v6, v7
	v_cvt_pk_bf16_f32 v7, v12, v13
	v_mfma_f32_32x32x16_bf16 v[112:127], v[20:23], v[0:3], v[112:127]
	v_mul_f32_e32 v0, v54, v52
	v_mul_f32_e32 v197, v0, v55
	v_mfma_f32_32x32x16_bf16 v[64:79], v[40:43], v[4:7], v[64:79]
	v_mfma_f32_32x32x16_bf16 v[80:95], v[36:39], v[4:7], v[80:95]
	s_nop 10
	v_mov_b64_e32 v[48:49], v[64:65]
	v_mov_b64_e32 v[50:51], v[66:67]
	v_mov_b64_e32 v[52:53], v[68:69]
	v_mov_b64_e32 v[54:55], v[70:71]
	v_mov_b64_e32 v[56:57], v[72:73]
	v_mov_b64_e32 v[58:59], v[74:75]
	v_mov_b64_e32 v[60:61], v[76:77]
	v_mfma_f32_32x32x16_bf16 v[96:111], v[28:31], v[4:7], v[96:111]
	v_mov_b64_e32 v[32:33], v[80:81]
	v_mov_b64_e32 v[34:35], v[82:83]
	v_mov_b64_e32 v[36:37], v[84:85]
	v_mov_b64_e32 v[38:39], v[86:87]
	v_mov_b64_e32 v[40:41], v[88:89]
	v_mov_b64_e32 v[42:43], v[90:91]
	v_mov_b64_e32 v[44:45], v[92:93]
	v_mfma_f32_32x32x16_bf16 v[112:127], v[16:19], v[4:7], v[112:127]
	s_nop 3
	v_mov_b64_e32 v[16:17], v[96:97]
	v_mov_b64_e32 v[18:19], v[98:99]
	v_mov_b64_e32 v[20:21], v[100:101]
	v_mov_b64_e32 v[22:23], v[102:103]
	v_mov_b64_e32 v[24:25], v[104:105]
	v_mov_b64_e32 v[26:27], v[106:107]
	v_mov_b64_e32 v[28:29], v[108:109]
	s_nop 0
	v_mov_b64_e32 v[0:1], v[112:113]
	v_mov_b64_e32 v[2:3], v[114:115]
	v_mov_b64_e32 v[4:5], v[116:117]
	v_mov_b64_e32 v[6:7], v[118:119]
	v_mov_b64_e32 v[8:9], v[120:121]
	v_mov_b64_e32 v[10:11], v[122:123]
	v_mov_b64_e32 v[12:13], v[124:125]
	v_mov_b64_e32 v[14:15], v[126:127]
	v_mov_b64_e32 v[30:31], v[110:111]
	v_mov_b64_e32 v[46:47], v[94:95]
	v_mov_b64_e32 v[62:63], v[78:79]
	s_branch .LBB0_542
.Lsb_skip_A0:
	v_mov_b64_e32 v[78:79], v[62:63]
	v_mov_b64_e32 v[94:95], v[46:47]
	v_mov_b64_e32 v[110:111], v[30:31]
	v_mov_b64_e32 v[126:127], v[14:15]
	v_mov_b32_e32 v199, v197
	v_mov_b64_e32 v[76:77], v[60:61]
	v_mov_b64_e32 v[74:75], v[58:59]
	v_mov_b64_e32 v[72:73], v[56:57]
	v_mov_b64_e32 v[70:71], v[54:55]
	v_mov_b64_e32 v[68:69], v[52:53]
	v_mov_b64_e32 v[66:67], v[50:51]
	v_mov_b64_e32 v[64:65], v[48:49]
	v_mov_b64_e32 v[92:93], v[44:45]
	v_mov_b64_e32 v[90:91], v[42:43]
	v_mov_b64_e32 v[88:89], v[40:41]
	v_mov_b64_e32 v[86:87], v[38:39]
	v_mov_b64_e32 v[84:85], v[36:37]
	v_mov_b64_e32 v[82:83], v[34:35]
	v_mov_b64_e32 v[80:81], v[32:33]
	v_mov_b64_e32 v[108:109], v[28:29]
	v_mov_b64_e32 v[106:107], v[26:27]
	v_mov_b64_e32 v[104:105], v[24:25]
	v_mov_b64_e32 v[102:103], v[22:23]
	v_mov_b64_e32 v[100:101], v[20:21]
	v_mov_b64_e32 v[98:99], v[18:19]
	v_mov_b64_e32 v[96:97], v[16:17]
	v_mov_b64_e32 v[124:125], v[12:13]
	v_mov_b64_e32 v[122:123], v[10:11]
	v_mov_b64_e32 v[120:121], v[8:9]
	v_mov_b64_e32 v[118:119], v[6:7]
	v_mov_b64_e32 v[116:117], v[4:5]
	v_mov_b64_e32 v[114:115], v[2:3]
	v_mov_b64_e32 v[112:113], v[0:1]
	s_branch .LBB0_562
.Lsb_skip_B0:
	v_mov_b64_e32 v[48:49], v[64:65]
	v_mov_b64_e32 v[32:33], v[80:81]
	v_mov_b64_e32 v[16:17], v[96:97]
	v_mov_b64_e32 v[0:1], v[112:113]
	v_mov_b32_e32 v197, v199
	v_mov_b64_e32 v[50:51], v[66:67]
	v_mov_b64_e32 v[52:53], v[68:69]
	v_mov_b64_e32 v[54:55], v[70:71]
	v_mov_b64_e32 v[56:57], v[72:73]
	v_mov_b64_e32 v[58:59], v[74:75]
	v_mov_b64_e32 v[60:61], v[76:77]
	v_mov_b64_e32 v[62:63], v[78:79]
	v_mov_b64_e32 v[34:35], v[82:83]
	v_mov_b64_e32 v[36:37], v[84:85]
	v_mov_b64_e32 v[38:39], v[86:87]
	v_mov_b64_e32 v[40:41], v[88:89]
	v_mov_b64_e32 v[42:43], v[90:91]
	v_mov_b64_e32 v[44:45], v[92:93]
	v_mov_b64_e32 v[46:47], v[94:95]
	v_mov_b64_e32 v[18:19], v[98:99]
	v_mov_b64_e32 v[20:21], v[100:101]
	v_mov_b64_e32 v[22:23], v[102:103]
	v_mov_b64_e32 v[24:25], v[104:105]
	v_mov_b64_e32 v[26:27], v[106:107]
	v_mov_b64_e32 v[28:29], v[108:109]
	v_mov_b64_e32 v[30:31], v[110:111]
	v_mov_b64_e32 v[2:3], v[114:115]
	v_mov_b64_e32 v[4:5], v[116:117]
	v_mov_b64_e32 v[6:7], v[118:119]
	v_mov_b64_e32 v[8:9], v[120:121]
	v_mov_b64_e32 v[10:11], v[122:123]
	v_mov_b64_e32 v[12:13], v[124:125]
	v_mov_b64_e32 v[14:15], v[126:127]
	s_branch .LBB0_568

; DEV void sb_block(const Params& p, int item) {
;     ...
;   for (int n = 0; n < nsteps; ++n) {
;     const int j = nsteps - 1 - n, buf = n & 3;
;     asm volatile("s_waitcnt vmcnt(8)" ::: "memory");
;     __builtin_amdgcn_s_barrier();
;     asm volatile("" ::: "memory");
;     { const int jn = j > 3 ? j - 3 : 0; SB_DMA(jn, (n + 3) & 3); }
.LBB0_1195:
	s_mov_b32 s32, 0x42f00000
	s_max_i32 s66, s71, 3
	s_lshl_b32 s66, s66, 6
	s_waitcnt vmcnt(8)
	s_barrier
	s_add_i32 s92, s66, 0xffffff40
	s_add_i32 s66, s33, 0x18000
	s_and_b32 s66, s66, 0x18000
	v_lshl_add_u64 v[64:65], s[92:93], 1, v[180:181]
	v_add_u32_e32 v66, s66, v204
	s_mov_b64 s[66:67], -1
	s_and_b64 vcc, exec, s[0:1]
	s_cbranch_vccz .LBB0_1203
	v_readlane_b32 s66, v252, 7
	v_add_u32_e32 v67, s3, v66
	v_readlane_b32 s67, v252, 8
	v_add_u32_e32 v67, 0x4000, v67
	s_nop 0
	v_lshl_add_u64 v[68:69], v[64:65], 0, s[66:67]
	v_readfirstlane_b32 s66, v67
	v_lshl_add_u64 v[68:69], v[68:69], 0, v[176:177]
	s_mov_b32 m0, s66
	s_nop 0
	global_load_lds_dwordx4 v[68:69], off
	s_cbranch_execz .LBB0_1204

; DEV f32x16 mfma32(bf16x8 a, bf16x8 b, f32x16 c) { return __builtin_amdgcn_mfma_f32_32x32x16_bf16(a, b, c, 0, 0, 0); }
; template <bool DIAG>
; DEV void sb_tile(const char* lk, const char* lv, const int ko0, const int vo0, const bf16x8 (&qf)[8], f32x16 (&O)[4], float& accp,
;                  const int l31, const int hh) {
;   f32x16 z;
;   for (int g = 0; g < 16; ++g) z[g] = 0.f;
;   {
;     bf16x8 kf[8];
; #pragma unroll
;     for (int s = 0; s < 8; ++s) kf[s] = *(const bf16x8*)(lk + (ko0 ^ (32 * s)));
;     __builtin_amdgcn_sched_barrier(0);
; #pragma unroll
;     for (int s = 0; s < 8; ++s) z = mfma32(kf[s], qf[s], z);
;   }
;   bf16x8 vf[4][2];
; #pragma unroll
;   for (int d = 0; d < 4; ++d) { vf[d][0] = *(const bf16x8*)(lv + d * 4096 + vo0); vf[d][1] = *(const bf16x8*)(lv + d * 4096 + (vo0 ^ 32)); }
;   __builtin_amdgcn_sched_barrier(0);
;   float be[16], om[16];
; #pragma unroll
;   for (int g = 0; g < 16; ++g) {
;     const float e = __builtin_amdgcn_exp2f(fminf(-z[g], 120.f));
;     be[g] = __builtin_amdgcn_rcpf(1.f + e);
;     om[g] = e * be[g];
;     if (DIAG) { const int kl = (g & 3) + 8 * (g >> 2) + 4 * hh; if (kl >= l31) { be[g] = 0.f; om[g] = 1.f; } }
;   }
; DEV void sb_block(const Params& p, int item) {
;     ...
;     if (2 * j + 1 == qt) sb_tile<true>(lb_ + 32 * 256, lb_, ko0, vo0 ^ 64, qf, O, accp, l31, hh);
;     else if (2 * j + 1 < qt) sb_tile<false>(lb_ + 32 * 256, lb_, ko0, vo0 ^ 64, qf, O, accp, l31, hh);
.LBB0_1211:
	s_and_b32 s66, s33, 0x18000
	s_add_i32 s92, s66, 0
	s_add_i32 s90, s74, s69
	v_mov_b32_e32 v168, v205
	v_mov_b32_e32 v193, v206
	s_cmp_lg_u32 s89, s69
	s_mov_b64 s[66:67], -1
	s_cbranch_scc0 .LBB0_1215
	s_add_i32 s66, s90, 7
	s_cmp_ge_i32 s66, s76
	s_cbranch_scc1 .Lsb_skip_A1
	v_add_u32_e32 v64, s92, v168
	v_xad_u32 v68, v168, 32, s92
	ds_read_b128 v[64:67], v64 offset:8192
	ds_read_b128 v[80:83], v68 offset:8192
	v_xad_u32 v68, v168, 64, s92
	v_xor_b32_e32 v69, 0x60, v168
	v_add_u32_e32 v69, s92, v69
	ds_read_b128 v[84:87], v68 offset:8192
	ds_read_b128 v[88:91], v69 offset:8192
	v_xor_b32_e32 v68, 0x80, v168
	v_add_u32_e32 v68, s92, v68
	v_xor_b32_e32 v69, 0xa0, v168
	v_add_u32_e32 v69, s92, v69
	ds_read_b128 v[92:95], v68 offset:8192
	ds_read_b128 v[96:99], v69 offset:8192
	v_xor_b32_e32 v68, 0xc0, v168
	v_add_u32_e32 v68, s92, v68
	v_xor_b32_e32 v69, 0xe0, v168
	v_add_u32_e32 v69, s92, v69
	ds_read_b128 v[100:103], v68 offset:8192
	ds_read_b128 v[104:107], v69 offset:8192
	s_waitcnt lgkmcnt(0)
	v_mfma_f32_32x32x16_bf16 v[64:79], v[64:67], v[128:131], 0
	v_mfma_f32_32x32x16_bf16 v[64:79], v[80:83], v[132:135], v[64:79]
	v_xor_b32_e32 v80, 0x60, v193
	v_mfma_f32_32x32x16_bf16 v[64:79], v[84:87], v[136:139], v[64:79]
	v_mfma_f32_32x32x16_bf16 v[64:79], v[88:91], v[140:143], v[64:79]
	v_xad_u32 v88, v193, 64, s92
	v_add_u32_e32 v89, s92, v80
	v_mfma_f32_32x32x16_bf16 v[64:79], v[92:95], v[144:147], v[64:79]
	v_mfma_f32_32x32x16_bf16 v[64:79], v[96:99], v[148:151], v[64:79]
	v_mfma_f32_32x32x16_bf16 v[64:79], v[100:103], v[152:155], v[64:79]
	ds_read_b128 v[84:87], v88
	ds_read_b128 v[96:99], v88 offset:4096
	ds_read_b128 v[80:83], v89
	ds_read_b128 v[100:103], v89 offset:4096
	ds_read_b128 v[112:115], v88 offset:8192
	ds_read_b128 v[164:167], v88 offset:12288
	ds_read_b128 v[116:119], v89 offset:8192
	ds_read_b128 v[160:163], v89 offset:12288
	v_mfma_f32_32x32x16_bf16 v[64:79], v[104:107], v[156:159], v[64:79]
	s_nop 11
	v_min_f32_e64 v68, -v68, s32
	v_exp_f32_e32 v90, v68
	v_min_f32_e64 v68, -v69, s32
	v_exp_f32_e32 v91, v68
	v_add_f32_e32 v68, 1.0, v90
	v_min_f32_e64 v73, -v73, s32
	v_add_f32_e32 v69, 1.0, v91
	v_rcp_f32_e32 v68, v68
	v_rcp_f32_e32 v69, v69
	v_exp_f32_e32 v104, v73
	v_max_f32_e64 v73, -v74, -v74
	v_max_f32_e64 v74, -v75, -v75
	v_min_f32_e64 v72, -v72, s32
	v_min_f32_e32 v74, 0x42f00000, v74
	v_min_f32_e64 v75, -v77, s32
	v_max_f32_e64 v77, -v79, -v79
	v_and_b32_e32 v79, 64, v219
	v_exp_f32_e32 v72, v72
	v_exp_f32_e32 v105, v74
	v_max_f32_e64 v74, -v76, -v76
	v_exp_f32_e32 v76, v75
	v_max_f32_e64 v75, -v78, -v78
	v_xor_b32_e32 v78, 32, v219
	v_add_u32_e32 v79, 64, v79
	v_min_f32_e32 v73, 0x42f00000, v73
	v_cmp_lt_i32_e32 vcc, v78, v79
	v_pk_mul_f32 v[90:91], v[90:91], v[68:69]
	v_exp_f32_e32 v73, v73
	v_cndmask_b32_e32 v78, v219, v78, vcc
	v_lshlrev_b32_e32 v170, 2, v78
	v_pk_mul_f32 v[78:79], v[90:91], v[90:91] op_sel_hi:[0,1]
	v_add_f32_e32 v78, 1.0, v72
	v_rcp_f32_e32 v108, v78
	v_add_f32_e32 v78, 1.0, v104
	v_rcp_f32_e32 v110, v78
	v_add_f32_e32 v78, 1.0, v73
	v_rcp_f32_e32 v109, v78
	v_add_f32_e32 v78, 1.0, v105
	v_min_f32_e32 v74, 0x42f00000, v74
	v_rcp_f32_e32 v111, v78
	v_exp_f32_e32 v74, v74
	v_min_f32_e32 v75, 0x42f00000, v75
	v_exp_f32_e32 v75, v75
	v_min_f32_e32 v77, 0x42f00000, v77
	v_exp_f32_e32 v77, v77
	v_pk_mul_f32 v[72:73], v[72:73], v[108:109]
	v_pk_mul_f32 v[104:105], v[104:105], v[110:111]
	v_pk_mul_f32 v[120:121], v[72:73], v[104:105]
	v_add_f32_e32 v72, 1.0, v74
	v_rcp_f32_e32 v122, v72
	v_add_f32_e32 v72, 1.0, v76
	v_rcp_f32_e32 v124, v72
	v_add_f32_e32 v72, 1.0, v75
	v_min_f32_e64 v70, -v70, s32
	v_rcp_f32_e32 v123, v72
	v_add_f32_e32 v72, 1.0, v77
	v_exp_f32_e32 v92, v70
	v_rcp_f32_e32 v125, v72
	v_min_f32_e64 v70, -v71, s32
	v_min_f32_e64 v67, -v67, s32
	v_exp_f32_e32 v93, v70
	v_min_f32_e64 v64, -v64, s32
	v_exp_f32_e32 v196, v67
	v_exp_f32_e32 v88, v64
	v_pk_mul_f32 v[74:75], v[74:75], v[122:123]
	v_pk_mul_f32 v[76:77], v[76:77], v[124:125]
	v_add_f32_e32 v70, 1.0, v92
	v_pk_mul_f32 v[126:127], v[74:75], v[76:77]
	v_add_f32_e32 v71, 1.0, v93
	v_mul_f32_e32 v72, v126, v127
	v_add_f32_e32 v67, 1.0, v196
	v_rcp_f32_e32 v70, v70
	v_rcp_f32_e32 v71, v71
	v_pk_mul_f32 v[120:121], v[120:121], v[120:121] op_sel:[0,1] op_sel_hi:[1,0]
	ds_bpermute_b32 v74, v170, v72
	v_add_f32_e32 v64, 1.0, v88
	v_min_f32_e64 v66, -v66, s32
	v_rcp_f32_e32 v67, v67
	ds_bpermute_b32 v121, v170, v120
	v_rcp_f32_e32 v64, v64
	v_min_f32_e64 v65, -v65, s32
	v_exp_f32_e32 v94, v66
	v_exp_f32_e32 v169, v65
	v_pk_mul_f32 v[92:93], v[92:93], v[70:71]
	s_waitcnt lgkmcnt(0)
; DEV f32x16 mfma32(bf16x8 a, bf16x8 b, f32x16 c) { return __builtin_amdgcn_mfma_f32_32x32x16_bf16(a, b, c, 0, 0, 0); }
; template <bool DIAG>
; DEV void sb_tile(const char* lk, const char* lv, const int ko0, const int vo0, const bf16x8 (&qf)[8], f32x16 (&O)[4], float& accp,
;                  const int l31, const int hh) {
;     ...
;   for (int q = 0; q < 4; ++q) { gp[q] = (om[4 * q] * om[4 * q + 1]) * (om[4 * q + 2] * om[4 * q + 3]); pp[q] = __shfl_xor(gp[q], 32); tot[q] = gp[q] * pp[q]; }
;   float suf[4];
;   suf[3] = accp; suf[2] = suf[3] * tot[3]; suf[1] = suf[2] * tot[2]; suf[0] = suf[1] * tot[1];
;   accp = suf[0] * tot[0];
;   f32x16 w;
; #pragma unroll
;   for (int q = 0; q < 4; ++q) {
;     float a = suf[q] * (hh == 0 ? pp[q] : 1.f);
;     w[4 * q + 3] = be[4 * q + 3] * a; a *= om[4 * q + 3];
;     w[4 * q + 2] = be[4 * q + 2] * a; a *= om[4 * q + 2];
;     w[4 * q + 1] = be[4 * q + 1] * a; a *= om[4 * q + 1];
;     w[4 * q + 0] = be[4 * q + 0] * a;
;   }
;   const bf16x8 w0 = cvt8<0>(w), w1 = cvt8<1>(w);
; #pragma unroll
;   for (int d = 0; d < 4; ++d) { O[d] = mfma32(vf[d][0], w0, O[d]); O[d] = mfma32(vf[d][1], w1, O[d]); }
	v_mul_f32_e32 v127, v72, v74
	v_pk_mul_f32 v[106:107], v[92:93], v[92:93] op_sel_hi:[0,1]
	v_mov_b32_e32 v126, v67
	v_add_f32_e32 v66, 1.0, v94
	v_mov_b32_e32 v89, v79
	v_cndmask_b32_e64 v72, 1.0, v121, s[10:11]
	v_mov_b32_e32 v78, v109
	v_mov_b32_e32 v79, v111
	v_mov_b32_e32 v109, v110
	v_pk_mul_f32 v[110:111], v[196:197], v[126:127]
	v_mov_b32_e32 v106, v64
	v_add_f32_e32 v65, 1.0, v169
	v_rcp_f32_e32 v66, v66
	v_mul_f32_e32 v127, v72, v111
	v_pk_mul_f32 v[88:89], v[88:89], v[106:107]
	v_rcp_f32_e32 v65, v65
	v_mul_f32_e32 v126, v105, v127
	ds_bpermute_b32 v105, v170, v89
	v_mov_b32_e32 v95, v120
	v_mov_b32_e32 v120, v66
	v_mul_f32_e32 v73, v73, v126
	v_pk_mul_f32 v[94:95], v[94:95], v[120:121]
	v_mul_f32_e32 v72, v104, v73
	v_mul_f32_e32 v104, v169, v65
	v_pk_mul_f32 v[120:121], v[94:95], v[110:111]
	s_waitcnt lgkmcnt(0)
	v_pk_mul_f32 v[88:89], v[88:89], v[104:105]
	v_cndmask_b32_e64 v90, 1.0, v105, s[10:11]
	v_pk_mul_f32 v[88:89], v[88:89], v[120:121]
	ds_bpermute_b32 v95, v170, v88
	v_cndmask_b32_e64 v74, 1.0, v74, s[10:11]
	v_pk_mul_f32 v[78:79], v[78:79], v[126:127]
	v_pk_mul_f32 v[72:73], v[108:109], v[72:73]
	v_cvt_pk_bf16_f32 v209, v78, v79
	s_waitcnt lgkmcnt(0)
	v_mul_f32_e32 v88, v88, v95
	v_mul_f32_e32 v199, v88, v89
	v_cndmask_b32_e64 v88, 1.0, v95, s[10:11]
	v_mul_f32_e32 v89, v88, v89
	v_mul_f32_e32 v88, v110, v89
	v_pk_mul_f32 v[66:67], v[66:67], v[88:89]
	v_mul_f32_e32 v89, v90, v121
	v_mul_f32_e32 v95, v94, v88
	v_mul_f32_e32 v88, v93, v89
	v_mul_f32_e32 v93, v92, v88
	v_mul_f32_e32 v92, v91, v93
	v_mul_f32_e32 v91, v197, v74
	v_mul_f32_e32 v90, v77, v91
	v_mul_f32_e32 v94, v104, v95
	v_mul_f32_e32 v75, v75, v90
	v_pk_mul_f32 v[64:65], v[64:65], v[94:95]
	v_pk_mul_f32 v[68:69], v[68:69], v[92:93]
	v_pk_mul_f32 v[70:71], v[70:71], v[88:89]
	v_mov_b32_e32 v88, v123
	v_mov_b32_e32 v123, v124
	v_mul_f32_e32 v74, v76, v75
	v_pk_mul_f32 v[74:75], v[122:123], v[74:75]
	v_cvt_pk_bf16_f32 v170, v64, v65
	v_cvt_pk_bf16_f32 v171, v66, v67
	v_cvt_pk_bf16_f32 v172, v68, v69
	v_cvt_pk_bf16_f32 v173, v70, v71
	v_cvt_pk_bf16_f32 v208, v72, v73
	v_cvt_pk_bf16_f32 v210, v74, v75
	v_mfma_f32_32x32x16_bf16 v[64:79], v[84:87], v[170:173], v[48:63]
	v_mov_b32_e32 v89, v125
	v_mul_f32_e64 v88, v88, v90
	v_mul_f32_e64 v89, v89, v91
	v_cvt_pk_bf16_f32 v211, v88, v89
	s_nop 1
	v_mfma_f32_32x32x16_bf16 v[64:79], v[80:83], v[208:211], v[64:79]
	v_mfma_f32_32x32x16_bf16 v[80:95], v[96:99], v[170:173], v[32:47]
	v_mfma_f32_32x32x16_bf16 v[80:95], v[100:103], v[208:211], v[80:95]
	v_mfma_f32_32x32x16_bf16 v[96:111], v[112:115], v[170:173], v[16:31]
	v_mfma_f32_32x32x16_bf16 v[96:111], v[116:119], v[208:211], v[96:111]
	v_mfma_f32_32x32x16_bf16 v[112:127], v[164:167], v[170:173], v[0:15]
	v_mfma_f32_32x32x16_bf16 v[112:127], v[160:163], v[208:211], v[112:127]

; DEV f32x16 mfma32(bf16x8 a, bf16x8 b, f32x16 c) { return __builtin_amdgcn_mfma_f32_32x32x16_bf16(a, b, c, 0, 0, 0); }
; template <bool DIAG>
; DEV void sb_tile(const char* lk, const char* lv, const int ko0, const int vo0, const bf16x8 (&qf)[8], f32x16 (&O)[4], float& accp,
;                  const int l31, const int hh) {
;   f32x16 z;
;   for (int g = 0; g < 16; ++g) z[g] = 0.f;
;   {
;     bf16x8 kf[8];
; #pragma unroll
;     for (int s = 0; s < 8; ++s) kf[s] = *(const bf16x8*)(lk + (ko0 ^ (32 * s)));
;     __builtin_amdgcn_sched_barrier(0);
; #pragma unroll
;     for (int s = 0; s < 8; ++s) z = mfma32(kf[s], qf[s], z);
;   }
;   bf16x8 vf[4][2];
; #pragma unroll
;   for (int d = 0; d < 4; ++d) { vf[d][0] = *(const bf16x8*)(lv + d * 4096 + vo0); vf[d][1] = *(const bf16x8*)(lv + d * 4096 + (vo0 ^ 32)); }
;   __builtin_amdgcn_sched_barrier(0);
;   float be[16], om[16];
; #pragma unroll
;   for (int g = 0; g < 16; ++g) {
;     const float e = __builtin_amdgcn_exp2f(fminf(-z[g], 120.f));
;     be[g] = __builtin_amdgcn_rcpf(1.f + e);
;     om[g] = e * be[g];
;     if (DIAG) { const int kl = (g & 3) + 8 * (g >> 2) + 4 * hh; if (kl >= l31) { be[g] = 0.f; om[g] = 1.f; } }
;   }
;   float gp[4], pp[4], tot[4];
; #pragma unroll
;   for (int q = 0; q < 4; ++q) { gp[q] = (om[4 * q] * om[4 * q + 1]) * (om[4 * q + 2] * om[4 * q + 3]); pp[q] = __shfl_xor(gp[q], 32); tot[q] = gp[q] * pp[q]; }
;   float suf[4];
;   suf[3] = accp; suf[2] = suf[3] * tot[3]; suf[1] = suf[2] * tot[2]; suf[0] = suf[1] * tot[1];
;   accp = suf[0] * tot[0];
;   f32x16 w;
; #pragma unroll
;   for (int q = 0; q < 4; ++q) {
;     float a = suf[q] * (hh == 0 ? pp[q] : 1.f);
;     w[4 * q + 3] = be[4 * q + 3] * a; a *= om[4 * q + 3];
;     w[4 * q + 2] = be[4 * q + 2] * a; a *= om[4 * q + 2];
;     w[4 * q + 1] = be[4 * q + 1] * a; a *= om[4 * q + 1];
;     w[4 * q + 0] = be[4 * q + 0] * a;
;   }
;   const bf16x8 w0 = cvt8<0>(w), w1 = cvt8<1>(w);
; #pragma unroll
;   for (int d = 0; d < 4; ++d) { O[d] = mfma32(vf[d][0], w0, O[d]); O[d] = mfma32(vf[d][1], w1, O[d]); }
; DEV void sb_block(const Params& p, int item) {
;     ...
;     else if (2 * j < qt) sb_tile<false>(lb_, lb_, ko0, vo0, qf, O, accp, l31, hh);
.LBB0_1217:
	s_cmp_lg_u32 s88, s69
	s_mov_b64 s[66:67], -1
	s_cbranch_scc0 .LBB0_1221
	s_add_i32 s90, s90, 6
	s_cmp_ge_i32 s90, s76
	s_cbranch_scc1 .Lsb_skip_B1
	ds_read_b128 v[0:3], v195
	ds_read_b128 v[16:19], v196
	ds_read_b128 v[20:23], v207
	ds_read_b128 v[24:27], v208
	ds_read_b128 v[28:31], v209
	ds_read_b128 v[32:35], v210
	ds_read_b128 v[36:39], v211
	ds_read_b128 v[40:43], v212
	s_waitcnt lgkmcnt(0)
	v_mfma_f32_32x32x16_bf16 v[0:15], v[0:3], v[128:131], 0
	v_mfma_f32_32x32x16_bf16 v[0:15], v[16:19], v[132:135], v[0:15]
	v_mfma_f32_32x32x16_bf16 v[0:15], v[20:23], v[136:139], v[0:15]
	v_mfma_f32_32x32x16_bf16 v[0:15], v[24:27], v[140:143], v[0:15]
	v_mfma_f32_32x32x16_bf16 v[0:15], v[28:31], v[144:147], v[0:15]
	v_mfma_f32_32x32x16_bf16 v[0:15], v[32:35], v[148:151], v[0:15]
	v_add_u32_e32 v32, s92, v193
	v_xad_u32 v33, v193, 32, s92
	ds_read_b128 v[28:31], v32
	ds_read_b128 v[16:19], v32 offset:4096
	ds_read_b128 v[24:27], v33
	ds_read_b128 v[20:23], v33 offset:4096
	ds_read_b128 v[168:171], v32 offset:8192
	ds_read_b128 v[164:167], v32 offset:12288
	ds_read_b128 v[172:175], v33 offset:8192
	ds_read_b128 v[160:163], v33 offset:12288
	v_mfma_f32_32x32x16_bf16 v[0:15], v[36:39], v[152:155], v[0:15]
	v_mfma_f32_32x32x16_bf16 v[0:15], v[40:43], v[156:159], v[0:15]
	s_nop 11
	v_min_f32_e64 v4, -v4, s32
	v_exp_f32_e32 v34, v4
	v_min_f32_e64 v4, -v5, s32
	v_exp_f32_e32 v35, v4
	v_add_f32_e32 v4, 1.0, v34
	v_min_f32_e64 v9, -v9, s32
	v_add_f32_e32 v5, 1.0, v35
	v_rcp_f32_e32 v4, v4
	v_rcp_f32_e32 v5, v5
	v_exp_f32_e32 v40, v9
	v_max_f32_e64 v9, -v10, -v10
	v_max_f32_e64 v10, -v11, -v11
	v_min_f32_e64 v8, -v8, s32
	v_min_f32_e32 v10, 0x42f00000, v10
	v_min_f32_e64 v11, -v13, s32
	v_max_f32_e64 v13, -v15, -v15
	v_and_b32_e32 v15, 64, v219
	v_exp_f32_e32 v8, v8
	v_exp_f32_e32 v41, v10
	v_max_f32_e64 v10, -v12, -v12
	v_exp_f32_e32 v12, v11
	v_max_f32_e64 v11, -v14, -v14
	v_xor_b32_e32 v14, 32, v219
	v_add_u32_e32 v15, 64, v15
	v_min_f32_e32 v9, 0x42f00000, v9
	v_cmp_lt_i32_e32 vcc, v14, v15
	v_pk_mul_f32 v[34:35], v[34:35], v[4:5]
	v_exp_f32_e32 v9, v9
	v_cndmask_b32_e32 v14, v219, v14, vcc
	v_lshlrev_b32_e32 v57, 2, v14
	v_pk_mul_f32 v[14:15], v[34:35], v[34:35] op_sel_hi:[0,1]
	v_add_f32_e32 v14, 1.0, v8
	v_rcp_f32_e32 v44, v14
	v_add_f32_e32 v14, 1.0, v40
	v_rcp_f32_e32 v46, v14
	v_add_f32_e32 v14, 1.0, v9
	v_rcp_f32_e32 v45, v14
	v_add_f32_e32 v14, 1.0, v41
	v_min_f32_e32 v10, 0x42f00000, v10
	v_rcp_f32_e32 v47, v14
	v_exp_f32_e32 v10, v10
	v_min_f32_e32 v11, 0x42f00000, v11
	v_exp_f32_e32 v11, v11
	v_min_f32_e32 v13, 0x42f00000, v13
	v_exp_f32_e32 v13, v13
	v_pk_mul_f32 v[8:9], v[8:9], v[44:45]
	v_pk_mul_f32 v[40:41], v[40:41], v[46:47]
	v_pk_mul_f32 v[48:49], v[8:9], v[40:41]
	v_add_f32_e32 v8, 1.0, v10
	v_rcp_f32_e32 v50, v8
	v_add_f32_e32 v8, 1.0, v12
	v_rcp_f32_e32 v52, v8
	v_add_f32_e32 v8, 1.0, v11
	v_min_f32_e64 v6, -v6, s32
	v_rcp_f32_e32 v51, v8
	v_add_f32_e32 v8, 1.0, v13
	v_exp_f32_e32 v36, v6
	v_rcp_f32_e32 v53, v8
	v_min_f32_e64 v6, -v7, s32
	v_min_f32_e64 v3, -v3, s32
	v_exp_f32_e32 v37, v6
	v_min_f32_e64 v0, -v0, s32
	v_exp_f32_e32 v198, v3
	v_exp_f32_e32 v32, v0
	v_pk_mul_f32 v[10:11], v[10:11], v[50:51]
	v_pk_mul_f32 v[12:13], v[12:13], v[52:53]
	v_add_f32_e32 v6, 1.0, v36
	v_pk_mul_f32 v[54:55], v[10:11], v[12:13]
	v_add_f32_e32 v7, 1.0, v37
	v_mul_f32_e32 v8, v54, v55
	v_add_f32_e32 v3, 1.0, v198
	v_rcp_f32_e32 v6, v6
	v_rcp_f32_e32 v7, v7
	v_pk_mul_f32 v[48:49], v[48:49], v[48:49] op_sel:[0,1] op_sel_hi:[1,0]
	ds_bpermute_b32 v10, v57, v8
	v_add_f32_e32 v0, 1.0, v32
	v_min_f32_e64 v2, -v2, s32
	v_rcp_f32_e32 v3, v3
	ds_bpermute_b32 v49, v57, v48
	v_rcp_f32_e32 v0, v0
	v_min_f32_e64 v1, -v1, s32
	v_exp_f32_e32 v38, v2
	v_exp_f32_e32 v56, v1
	v_pk_mul_f32 v[36:37], v[36:37], v[6:7]
	s_waitcnt lgkmcnt(0)
	v_mul_f32_e32 v55, v8, v10
	v_pk_mul_f32 v[42:43], v[36:37], v[36:37] op_sel_hi:[0,1]
	v_mov_b32_e32 v54, v3
	v_add_f32_e32 v2, 1.0, v38
	v_mov_b32_e32 v33, v15
	v_cndmask_b32_e64 v8, 1.0, v49, s[10:11]
	v_mov_b32_e32 v14, v45
	v_mov_b32_e32 v15, v47
	v_mov_b32_e32 v45, v46
	v_pk_mul_f32 v[46:47], v[198:199], v[54:55]
	v_mov_b32_e32 v42, v0
	v_add_f32_e32 v1, 1.0, v56
	v_rcp_f32_e32 v2, v2
	v_mul_f32_e32 v55, v8, v47
	v_pk_mul_f32 v[32:33], v[32:33], v[42:43]
	v_rcp_f32_e32 v1, v1
	v_mul_f32_e32 v54, v41, v55
	ds_bpermute_b32 v41, v57, v33
	v_mov_b32_e32 v39, v48
	v_mov_b32_e32 v48, v2
	v_mul_f32_e32 v9, v9, v54
	v_pk_mul_f32 v[38:39], v[38:39], v[48:49]
	v_mul_f32_e32 v8, v40, v9
	v_mul_f32_e32 v40, v56, v1
	v_pk_mul_f32 v[48:49], v[38:39], v[46:47]
	s_waitcnt lgkmcnt(0)
	v_pk_mul_f32 v[32:33], v[32:33], v[40:41]
	v_cndmask_b32_e64 v34, 1.0, v41, s[10:11]
	v_pk_mul_f32 v[32:33], v[32:33], v[48:49]
	ds_bpermute_b32 v39, v57, v32
	v_cndmask_b32_e64 v10, 1.0, v10, s[10:11]
	v_pk_mul_f32 v[14:15], v[14:15], v[54:55]
	v_pk_mul_f32 v[8:9], v[44:45], v[8:9]
	v_cvt_pk_bf16_f32 v225, v14, v15
	s_waitcnt lgkmcnt(0)
	v_mul_f32_e32 v32, v32, v39
	v_mul_f32_e32 v197, v32, v33
	v_cndmask_b32_e64 v32, 1.0, v39, s[10:11]
	v_mul_f32_e32 v33, v32, v33
	v_mul_f32_e32 v32, v46, v33
	v_pk_mul_f32 v[2:3], v[2:3], v[32:33]
	v_mul_f32_e32 v33, v34, v49
	v_mul_f32_e32 v39, v38, v32
	v_mul_f32_e32 v32, v37, v33
	v_mul_f32_e32 v37, v36, v32
	v_mul_f32_e32 v36, v35, v37
	v_mul_f32_e32 v35, v199, v10
	v_mul_f32_e32 v38, v40, v39
	v_mul_f32_e32 v34, v13, v35
	v_pk_mul_f32 v[0:1], v[0:1], v[38:39]
	v_pk_mul_f32 v[4:5], v[4:5], v[36:37]
	v_pk_mul_f32 v[6:7], v[6:7], v[32:33]
	v_mov_b32_e32 v32, v51
	v_mov_b32_e32 v33, v53
	v_mul_f32_e32 v11, v11, v34
	v_pk_mul_f32 v[32:33], v[32:33], v[34:35]
	v_mov_b32_e32 v51, v52
	v_mul_f32_e32 v10, v12, v11
	v_cvt_pk_bf16_f32 v214, v0, v1
	v_cvt_pk_bf16_f32 v215, v2, v3
	v_cvt_pk_bf16_f32 v216, v4, v5
	v_cvt_pk_bf16_f32 v217, v6, v7
	v_pk_mul_f32 v[10:11], v[50:51], v[10:11]
	v_cvt_pk_bf16_f32 v227, v32, v33
	v_mfma_f32_32x32x16_bf16 v[48:63], v[28:31], v[214:217], v[64:79]
	v_cvt_pk_bf16_f32 v224, v8, v9
	v_cvt_pk_bf16_f32 v226, v10, v11
	v_mfma_f32_32x32x16_bf16 v[32:47], v[16:19], v[214:217], v[80:95]
	s_nop 0
	v_mfma_f32_32x32x16_bf16 v[48:63], v[24:27], v[224:227], v[48:63]
	v_mfma_f32_32x32x16_bf16 v[32:47], v[20:23], v[224:227], v[32:47]
	v_mfma_f32_32x32x16_bf16 v[16:31], v[168:171], v[214:217], v[96:111]
	v_mfma_f32_32x32x16_bf16 v[0:15], v[164:167], v[214:217], v[112:127]
	v_mfma_f32_32x32x16_bf16 v[16:31], v[172:175], v[224:227], v[16:31]
	v_mfma_f32_32x32x16_bf16 v[0:15], v[160:163], v[224:227], v[0:15]
